# B (MLA) loops: q blocks 8,9 held in idle VGPRs for the whole unit instead of re-read from LDS every tile (2 ds_read_b128 per tile fewer in the LDS-bound QK tail)
# speedup vs baseline: 1.0112x; 1.0050x over previous
; __device__ __forceinline__ float bf2f(unsigned short b) { return __uint_as_float(((unsigned)b) << 16); }
; __device__ __forceinline__ unsigned pk2(float lo, float hi) { return f2bf(lo) | (f2bf(hi) << 16); }
;     ...
;   const bf16_t* Qw = Qb + (long)(wid * QBLK + r32) * ldq + hi * 8;
;   char* qls = lds + LDS_Q_OFF + wid * 8192 + lane * 16;
; #pragma unroll
;   for (int d0 = 0; d0 < NDQ - NQL; ++d0) qr[d0] = *reinterpret_cast<const bf16x8*>(Qw + d0 * 16);
;   if constexpr (ROPEQ) {
;     static_assert(NDQ == 12 && NQL >= 4, "ROPEQ: MLA layout");
; #pragma unroll
;     for (int d0 = NDQ - NQL; d0 < 8; ++d0) *reinterpret_cast<bf16x8*>(qls + (d0 - (NDQ - NQL)) * 1024) = *reinterpret_cast<const bf16x8*>(Qw + d0 * 16);
;     const int qrow = q0 + wid * QBLK + r32;
; #pragma unroll
;     for (int pr = 0; pr < 2; ++pr) {
;       const bf16x8 xa = *reinterpret_cast<const bf16x8*>(Qw + (8 + pr) * 16), xb = *reinterpret_cast<const bf16x8*>(Qw + (10 + pr) * 16);
;       const float* cp = cosp + (size_t)qrow * 32 + pr * 16 + hi * 8; const float* sp = sinp + (size_t)qrow * 32 + pr * 16 + hi * 8;
;       const f32x4 c0 = *(const f32x4*)cp, c1 = *(const f32x4*)(cp + 4), s0 = *(const f32x4*)sp, s1 = *(const f32x4*)(sp + 4);
;       float ya[8], yb[8];
; #pragma unroll
;       for (int t = 0; t < 8; ++t) { const float x1 = bf2f((unsigned short)xa[t]), x2 = bf2f((unsigned short)xb[t]); const float c = t < 4 ? c0[t & 3] : c1[t & 3], sn = t < 4 ? s0[t & 3] : s1[t & 3];
;         ya[t] = x1 * c - x2 * sn; yb[t] = x2 * c + x1 * sn; }
;       u32x4 wa = {pk2(ya[0], ya[1]), pk2(ya[2], ya[3]), pk2(ya[4], ya[5]), pk2(ya[6], ya[7])}, wb = {pk2(yb[0], yb[1]), pk2(yb[2], yb[3]), pk2(yb[4], yb[5]), pk2(yb[6], yb[7])};
;       *reinterpret_cast<u32x4*>(qls + (8 + pr - (NDQ - NQL)) * 1024) = wa; *reinterpret_cast<u32x4*>(qls + (10 + pr - (NDQ - NQL)) * 1024) = wb; }
.LBB0_358:
	s_and_b32 s4, s63, 3
	s_lshl_b32 s5, s82, 3
	s_lshl_b32 s59, s4, 9
	s_lshr_b32 s4, s82, 3
	s_and_b32 s5, s5, 32
	s_add_i32 s4, s5, s4
	s_and_b32 s83, s82, 3
	s_lshl_b32 s58, s4, 8
	s_mul_i32 s4, s4, 0x60000
	s_mul_hi_i32 s5, s58, 0x600
	s_add_u32 s4, s45, s4
	s_addc_u32 s5, s46, s5
	s_mul_i32 s6, s83, 0x180
	s_add_u32 s64, s4, s6
	s_addc_u32 s65, s5, 0
	s_lshl_b32 s4, s83, 9
	v_readlane_b32 s6, v254, 19
	s_add_u32 s60, s47, s4
	v_readlane_b32 s7, v254, 20
	s_addc_u32 s61, s62, 0
	s_mov_b64 s[4:5], -1
	s_and_b64 vcc, exec, s[6:7]
	s_cbranch_vccz .LBB0_384
	v_readlane_b32 s4, v254, 8
	v_mbcnt_lo_u32_b32 v56, -1, 0
	v_mbcnt_hi_u32_b32 v56, -1, v56
	v_mov_b32_e32 v185, v1
	v_and_b32_e32 v0, 31, v56
	v_add_u32_e32 v30, s4, v56
	v_ashrrev_i32_e32 v4, 6, v30
	v_and_b32_e32 v2, 0x3fffffc0, v30
	v_lshlrev_b32_e32 v182, 5, v4
	v_bfe_u32 v198, v56, 5, 1
	v_lshl_add_u32 v183, v2, 2, s37
	v_or_b32_e32 v5, v182, v0
	v_mov_b64_e32 v[2:3], s[64:65]
	v_and_b32_e32 v57, 63, v56
	v_mad_i64_i32 v[2:3], s[4:5], v5, s1, v[2:3]
	v_lshlrev_b32_e32 v184, 4, v198
	v_lshl_add_u64 v[22:23], v[2:3], 0, v[184:185]
	v_lshlrev_b32_e32 v2, 13, v4
	v_lshlrev_b32_e32 v28, 4, v57
	v_readlane_b32 s4, v254, 58
	v_and_b32_e32 v6, 32, v56
	v_mov_b32_e32 v7, v1
	v_add3_u32 v199, s4, v2, v28
	v_or_b32_e32 v2, s58, v0
	v_add_u32_e32 v2, v2, v182
	v_ashrrev_i32_e32 v3, 31, v2
	v_lshlrev_b64 v[2:3], 7, v[2:3]
	v_lshl_add_u64 v[4:5], s[50:51], 0, v[2:3]
	v_lshl_add_u64 v[32:33], v[4:5], 0, v[6:7]
	v_lshl_add_u64 v[2:3], s[56:57], 0, v[2:3]
	s_waitcnt vmcnt(63) expcnt(7) lgkmcnt(15)
	s_barrier
	global_load_dwordx4 v[142:145], v[22:23], off
	global_load_dwordx4 v[138:141], v[22:23], off offset:32
	global_load_dwordx4 v[134:137], v[22:23], off offset:64
	global_load_dwordx4 v[130:133], v[22:23], off offset:96
	global_load_dwordx4 v[126:129], v[22:23], off offset:128
	global_load_dwordx4 v[122:125], v[22:23], off offset:160
	global_load_dwordx4 v[118:121], v[22:23], off offset:192
	global_load_dwordx4 v[114:117], v[22:23], off offset:224
	v_lshl_add_u64 v[34:35], v[2:3], 0, v[6:7]
	global_load_dwordx4 v[2:5], v[32:33], off offset:16
	global_load_dwordx4 v[6:9], v[32:33], off
	global_load_dwordx4 v[10:13], v[34:35], off offset:16
	global_load_dwordx4 v[14:17], v[34:35], off
	global_load_dwordx4 v[18:21], v[22:23], off offset:256
	global_load_dwordx4 v[24:27], v[22:23], off offset:320
	s_cmp_lg_u32 0, -1
	s_cselect_b32 s6, 0, 0
	s_cmp_lg_u32 s44, -1
	s_cselect_b32 s4, s44, 0
	v_mov_b32_e32 v29, v1
	s_movk_i32 s5, 0x70
	s_mov_b32 s96, -1
	v_and_b32_e32 v58, 7, v56
	s_waitcnt vmcnt(4)
	v_mov_b32_e32 v40, v6
	v_mov_b32_e32 v41, v8
	s_waitcnt vmcnt(2)
	v_mov_b32_e32 v42, v14
	s_waitcnt vmcnt(1)
	v_lshlrev_b32_e32 v37, 16, v19
	v_lshlrev_b32_e32 v36, 16, v18
	s_waitcnt vmcnt(0)
	v_lshlrev_b32_e32 v39, 16, v25
	v_lshlrev_b32_e32 v38, 16, v24
	v_and_b32_e32 v19, 0xffff0000, v19
	v_and_b32_e32 v18, 0xffff0000, v18
	v_and_b32_e32 v25, 0xffff0000, v25
	v_and_b32_e32 v24, 0xffff0000, v24
	v_mov_b32_e32 v43, v16
	v_mov_b32_e32 v16, v15
	v_mov_b32_e32 v8, v7
	v_pk_mul_f32 v[6:7], v[16:17], v[18:19]
	v_pk_mul_f32 v[14:15], v[42:43], v[38:39]
	v_pk_mul_f32 v[16:17], v[16:17], v[24:25]
	v_pk_mul_f32 v[44:45], v[42:43], v[36:37]
	v_pk_fma_f32 v[6:7], v[8:9], v[24:25], v[6:7]
	v_pk_fma_f32 v[14:15], v[40:41], v[36:37], v[14:15] neg_lo:[0,0,1] neg_hi:[0,0,1]
	v_pk_fma_f32 v[8:9], v[8:9], v[18:19], v[16:17] neg_lo:[0,0,1] neg_hi:[0,0,1]
	v_lshlrev_b32_e32 v17, 16, v21
	v_lshlrev_b32_e32 v16, 16, v20
	v_and_b32_e32 v21, 0xffff0000, v21
	v_and_b32_e32 v20, 0xffff0000, v20
	v_and_b32_e32 v25, 0xffff0000, v27
	v_and_b32_e32 v24, 0xffff0000, v26
	v_mov_b32_e32 v37, v12
	v_mov_b32_e32 v12, v11
	v_lshlrev_b32_e32 v19, 16, v27
	v_lshlrev_b32_e32 v18, 16, v26
	v_mov_b32_e32 v26, v2
	v_mov_b32_e32 v27, v4
	v_mov_b32_e32 v36, v10
	v_mov_b32_e32 v4, v3
	v_pk_mul_f32 v[2:3], v[12:13], v[20:21]
	v_pk_mul_f32 v[12:13], v[12:13], v[24:25]
	v_pk_fma_f32 v[10:11], v[4:5], v[24:25], v[2:3]
	v_pk_mul_f32 v[2:3], v[36:37], v[18:19]
	v_pk_fma_f32 v[4:5], v[4:5], v[20:21], v[12:13] neg_lo:[0,0,1] neg_hi:[0,0,1]
	v_pk_fma_f32 v[44:45], v[40:41], v[38:39], v[44:45]
	v_pk_mul_f32 v[38:39], v[36:37], v[16:17]
	v_pk_fma_f32 v[2:3], v[26:27], v[16:17], v[2:3] neg_lo:[0,0,1] neg_hi:[0,0,1]
	v_bfe_u32 v12, v5, 16, 1
	v_bfe_u32 v13, v4, 16, 1
	v_bfe_u32 v16, v9, 16, 1
	v_bfe_u32 v17, v8, 16, 1
	v_add3_u32 v8, v8, v17, s0
	v_add3_u32 v9, v9, v16, s0
	v_add3_u32 v4, v4, v13, s0
	v_add3_u32 v5, v5, v12, s0
	v_bfe_u32 v12, v14, 16, 1
	v_bfe_u32 v13, v15, 16, 1
	v_bfe_u32 v16, v2, 16, 1
	v_bfe_u32 v17, v3, 16, 1
	v_add3_u32 v3, v3, v17, s0
	v_add3_u32 v2, v2, v16, s0
	v_add3_u32 v13, v15, v13, s0
	v_add3_u32 v12, v14, v12, s0
	v_lshrrev_b32_e32 v12, 16, v12
	v_lshrrev_b32_e32 v13, 16, v13
	v_lshrrev_b32_e32 v2, 16, v2
	v_lshrrev_b32_e32 v3, 16, v3
	v_pk_fma_f32 v[38:39], v[26:27], v[18:19], v[38:39]
	v_and_or_b32 v5, v5, s34, v3
	v_and_or_b32 v4, v4, s34, v2
	v_and_or_b32 v3, v9, s34, v13
	v_and_or_b32 v2, v8, s34, v12
	v_bfe_u32 v8, v11, 16, 1
	v_bfe_u32 v9, v10, 16, 1
	v_bfe_u32 v12, v7, 16, 1
	v_bfe_u32 v13, v6, 16, 1
	v_add3_u32 v6, v6, v13, s0
	v_add3_u32 v7, v7, v12, s0
	v_add3_u32 v10, v10, v9, s0
	v_add3_u32 v8, v11, v8, s0
	v_bfe_u32 v9, v44, 16, 1
	v_bfe_u32 v11, v45, 16, 1
	v_bfe_u32 v12, v38, 16, 1
	v_bfe_u32 v13, v39, 16, 1
	v_add3_u32 v13, v39, v13, s0
	v_add3_u32 v12, v38, v12, s0
	v_add3_u32 v11, v45, v11, s0
	v_add3_u32 v9, v44, v9, s0
	v_lshrrev_b32_e32 v14, 16, v9
	v_lshrrev_b32_e32 v11, 16, v11
	v_lshrrev_b32_e32 v12, 16, v12
	v_lshrrev_b32_e32 v9, 16, v13
	v_and_or_b32 v9, v8, s34, v9
	v_and_or_b32 v8, v10, s34, v12
	v_and_or_b32 v7, v7, s34, v11
	v_and_or_b32 v6, v6, s34, v14
	ds_write_b128 v199, v[2:5]
	ds_write_b128 v199, v[6:9] offset:2048
	global_load_dwordx4 v[2:5], v[32:33], off offset:80
	global_load_dwordx4 v[10:13], v[32:33], off offset:64
	global_load_dwordx4 v[6:9], v[34:35], off offset:80
	global_load_dwordx4 v[14:17], v[34:35], off offset:64
	global_load_dwordx4 v[18:21], v[22:23], off offset:288
	s_waitcnt vmcnt(3)
; __device__ __forceinline__ float bf2f(unsigned short b) { return __uint_as_float(((unsigned)b) << 16); }
; __device__ __forceinline__ unsigned pk2(float lo, float hi) { return f2bf(lo) | (f2bf(hi) << 16); }
; __device__ __forceinline__ int v_st(int k, int c) { const int kk = (k & ~0xC) | ((k & 4) << 1) | ((k & 8) >> 1); return ((kk >> 3) * 4 + (c >> 5)) * 512 + ((kk & 7) * 32 + (c & 31)) * 2; }
; __device__ __forceinline__ int v_rd_base(int lane) { return ((lane & 3) << 3) | (((lane >> 2) & 3) << 6) | (((lane >> 4) & 1) << 5) | (((lane >> 5) & 1) << 8); }
;     ...
;       const bf16x8 xa = *reinterpret_cast<const bf16x8*>(Qw + (8 + pr) * 16), xb = *reinterpret_cast<const bf16x8*>(Qw + (10 + pr) * 16);
;       const float* cp = cosp + (size_t)qrow * 32 + pr * 16 + hi * 8; const float* sp = sinp + (size_t)qrow * 32 + pr * 16 + hi * 8;
;       const f32x4 c0 = *(const f32x4*)cp, c1 = *(const f32x4*)(cp + 4), s0 = *(const f32x4*)sp, s1 = *(const f32x4*)(sp + 4);
;       float ya[8], yb[8];
; #pragma unroll
;       for (int t = 0; t < 8; ++t) { const float x1 = bf2f((unsigned short)xa[t]), x2 = bf2f((unsigned short)xb[t]); const float c = t < 4 ? c0[t & 3] : c1[t & 3], sn = t < 4 ? s0[t & 3] : s1[t & 3];
;         ya[t] = x1 * c - x2 * sn; yb[t] = x2 * c + x1 * sn; }
;       u32x4 wa = {pk2(ya[0], ya[1]), pk2(ya[2], ya[3]), pk2(ya[4], ya[5]), pk2(ya[6], ya[7])}, wb = {pk2(yb[0], yb[1]), pk2(yb[2], yb[3]), pk2(yb[4], yb[5]), pk2(yb[6], yb[7])};
;       *reinterpret_cast<u32x4*>(qls + (8 + pr - (NDQ - NQL)) * 1024) = wa; *reinterpret_cast<u32x4*>(qls + (10 + pr - (NDQ - NQL)) * 1024) = wb; }
;     ...
;   const int sr = tid >> 4, sc = (tid & 15) * 8, vst0 = v_st(sr, sc), vst1 = v_st(32 + sr, sc);
;   const int sr8 = tid >> 3, sc8 = (tid & 7) * 8;
;   const int vb0 = (int)(uintptr_t)V_lds + v_rd_base(lane);
;   const int qlane = q0 + wid * QBLK + r32;
;   struct { bf16x8 vs0, vs1, ks0, ks1, ks2; } sr_[SDEPTH];
;   constexpr int SWM = (NDQ == 8) ? 15 : 7;
;     ...
;   f32x16 pA0, pA1, pB0, pB1; float alA, alB; bf16x8 pa0, pa1, pa2, pa3; const int NT = nkeys / KVBLK;
;   const int kb0 = (int)(uintptr_t)K_lds + r32 * ROWB + (((r32 & SWM) << 4) ^ (hi << 4));
;   const int qa0 = (int)(uintptr_t)qls;
;     ...
;   constexpr int SE = 0, SO = SDEPTH - 1;
;   SLOAD(SE, kbeg); asm volatile("s_waitcnt vmcnt(0)" ::: "memory"); SWRITE(0, SE); __syncthreads();
	v_mov_b32_e32 v34, v10
	global_load_dwordx4 v[22:25], v[22:23], off offset:352
	s_waitcnt vmcnt(2)
	v_mov_b32_e32 v36, v14
	s_waitcnt vmcnt(1)
	v_lshlrev_b32_e32 v27, 16, v19
	v_lshlrev_b32_e32 v26, 16, v18
	v_and_b32_e32 v19, 0xffff0000, v19
	v_and_b32_e32 v18, 0xffff0000, v18
	v_mov_b32_e32 v37, v16
	v_mov_b32_e32 v16, v15
	v_mov_b32_e32 v35, v12
	v_mov_b32_e32 v12, v11
	v_pk_mul_f32 v[10:11], v[16:17], v[18:19]
	v_pk_mul_f32 v[38:39], v[36:37], v[26:27]
	s_waitcnt vmcnt(0)
	v_lshlrev_b32_e32 v33, 16, v23
	v_lshlrev_b32_e32 v32, 16, v22
	v_and_b32_e32 v23, 0xffff0000, v23
	v_and_b32_e32 v22, 0xffff0000, v22
	v_pk_mul_f32 v[14:15], v[36:37], v[32:33]
	v_pk_mul_f32 v[16:17], v[16:17], v[22:23]
	v_pk_fma_f32 v[10:11], v[12:13], v[22:23], v[10:11]
	v_pk_fma_f32 v[14:15], v[34:35], v[26:27], v[14:15] neg_lo:[0,0,1] neg_hi:[0,0,1]
	v_pk_fma_f32 v[12:13], v[12:13], v[18:19], v[16:17] neg_lo:[0,0,1] neg_hi:[0,0,1]
	v_lshlrev_b32_e32 v17, 16, v21
	v_lshlrev_b32_e32 v16, 16, v20
	v_and_b32_e32 v21, 0xffff0000, v21
	v_and_b32_e32 v20, 0xffff0000, v20
	v_and_b32_e32 v23, 0xffff0000, v25
	v_and_b32_e32 v22, 0xffff0000, v24
	v_mov_b32_e32 v27, v8
	v_mov_b32_e32 v8, v7
	v_lshlrev_b32_e32 v19, 16, v25
	v_lshlrev_b32_e32 v18, 16, v24
	v_mov_b32_e32 v24, v2
	v_mov_b32_e32 v25, v4
	v_mov_b32_e32 v26, v6
	v_mov_b32_e32 v4, v3
	v_pk_mul_f32 v[2:3], v[8:9], v[20:21]
	v_pk_mul_f32 v[8:9], v[8:9], v[22:23]
	v_pk_fma_f32 v[6:7], v[4:5], v[22:23], v[2:3]
	v_pk_mul_f32 v[2:3], v[26:27], v[18:19]
	v_pk_fma_f32 v[4:5], v[4:5], v[20:21], v[8:9] neg_lo:[0,0,1] neg_hi:[0,0,1]
	v_pk_fma_f32 v[38:39], v[34:35], v[32:33], v[38:39]
	v_pk_mul_f32 v[32:33], v[26:27], v[16:17]
	v_pk_fma_f32 v[2:3], v[24:25], v[16:17], v[2:3] neg_lo:[0,0,1] neg_hi:[0,0,1]
	v_bfe_u32 v8, v5, 16, 1
	v_bfe_u32 v9, v4, 16, 1
	v_bfe_u32 v16, v13, 16, 1
	v_bfe_u32 v17, v12, 16, 1
	v_add3_u32 v12, v12, v17, s0
	v_add3_u32 v13, v13, v16, s0
	v_add3_u32 v4, v4, v9, s0
	v_add3_u32 v5, v5, v8, s0
	v_bfe_u32 v8, v14, 16, 1
	v_bfe_u32 v9, v15, 16, 1
	v_bfe_u32 v16, v2, 16, 1
	v_bfe_u32 v17, v3, 16, 1
	v_add3_u32 v3, v3, v17, s0
	v_add3_u32 v2, v2, v16, s0
	v_add3_u32 v9, v15, v9, s0
	v_add3_u32 v8, v14, v8, s0
	v_lshrrev_b32_e32 v8, 16, v8
	v_lshrrev_b32_e32 v9, 16, v9
	v_lshrrev_b32_e32 v2, 16, v2
	v_lshrrev_b32_e32 v3, 16, v3
	v_pk_fma_f32 v[32:33], v[24:25], v[18:19], v[32:33]
	v_and_or_b32 v5, v5, s34, v3
	v_and_or_b32 v4, v4, s34, v2
	v_and_or_b32 v3, v13, s34, v9
	v_and_or_b32 v2, v12, s34, v8
	v_bfe_u32 v8, v7, 16, 1
	v_bfe_u32 v9, v6, 16, 1
	v_bfe_u32 v12, v11, 16, 1
	v_bfe_u32 v13, v10, 16, 1
	v_add3_u32 v10, v10, v13, s0
	v_add3_u32 v11, v11, v12, s0
	v_add3_u32 v6, v6, v9, s0
	v_add3_u32 v7, v7, v8, s0
	v_bfe_u32 v8, v38, 16, 1
	v_bfe_u32 v9, v39, 16, 1
	v_bfe_u32 v12, v32, 16, 1
	v_bfe_u32 v13, v33, 16, 1
	v_add3_u32 v13, v33, v13, s0
	v_add3_u32 v12, v32, v12, s0
	v_add3_u32 v9, v39, v9, s0
	v_add3_u32 v8, v38, v8, s0
	v_lshrrev_b32_e32 v14, 16, v8
	v_lshrrev_b32_e32 v15, 16, v9
	v_lshrrev_b32_e32 v8, 16, v12
	v_lshrrev_b32_e32 v9, 16, v13
	v_ashrrev_i32_e32 v22, 4, v30
	v_and_or_b32 v9, v7, s34, v9
	v_and_or_b32 v8, v6, s34, v8
	v_and_or_b32 v7, v11, s34, v15
	v_and_or_b32 v6, v10, s34, v14
	ds_write_b128 v199, v[2:5] offset:1024
	ds_write_b128 v199, v[6:9] offset:3072
	v_and_b32_e32 v4, 0xfffff0, v22
	v_lshlrev_b32_e32 v5, 1, v22
	v_lshlrev_b32_e32 v2, 3, v56
	v_and_or_b32 v4, v22, 8, v4
	v_and_b32_e32 v3, 0x78, v2
	v_lshrrev_b32_e32 v5, 1, v22
	v_lshrrev_b32_e32 v4, 1, v4
	v_bfe_u32 v2, v2, 5, 2
	v_and_b32_e32 v6, 3, v22
	v_or_b32_e32 v4, v4, v2
	v_and_or_b32 v5, v22, 4, v6
	v_lshlrev_b32_e32 v24, 1, v3
	v_lshlrev_b32_e32 v4, 9, v4
	v_lshlrev_b32_e32 v5, 6, v5
	v_and_b32_e32 v3, 48, v24
	v_add_u32_e32 v6, 32, v22
	v_or3_b32 v31, v4, v5, v3
	v_and_b32_e32 v4, 0xfffff0, v6
	v_lshlrev_b32_e32 v7, 1, v6
	v_and_or_b32 v4, v6, 8, v4
	v_lshrrev_b32_e32 v4, 1, v4
	v_or_b32_e32 v2, v4, v2
	v_lshlrev_b32_e32 v2, 9, v2
	v_or3_b32 v32, v2, v5, v3
	v_lshlrev_b32_e32 v2, 3, v57
	v_and_b32_e32 v3, 0xc0, v28
	v_lshlrev_b32_e32 v4, 1, v56
	v_and_or_b32 v3, v2, 24, v3
	v_and_b32_e32 v4, 32, v4
	v_and_b32_e32 v2, 0x100, v2
	v_or3_b32 v59, v3, v4, v2
	v_bitop3_b32 v3, v198, v56, 7 bitop3:0x78
	v_ashrrev_i32_e32 v23, 31, v22
	v_mul_u32_u24_e32 v2, 0x180, v0
	v_lshlrev_b32_e32 v3, 4, v3
	v_lshlrev_b64 v[50:51], 11, v[22:23]
	v_add3_u32 v209, v2, s4, v3
	v_lshl_add_u64 v[2:3], s[60:61], 0, v[50:51]
	v_mov_b32_e32 v25, v1
	v_ashrrev_i32_e32 v26, 3, v30
	v_lshl_add_u64 v[52:53], v[2:3], 0, v[24:25]
	global_load_dwordx4 v[2:5], v[52:53], off offset:256
	v_ashrrev_i32_e32 v7, 31, v6
	v_ashrrev_i32_e32 v27, 31, v26
	v_lshlrev_b64 v[6:7], 11, v[6:7]
	v_lshlrev_b64 v[186:187], 7, v[26:27]
	v_lshlrev_b32_e32 v20, 4, v56
	v_lshl_add_u64 v[6:7], s[60:61], 0, v[6:7]
	v_lshl_add_u64 v[18:19], s[8:9], 0, v[186:187]
	v_and_b32_e32 v28, 0x70, v20
	v_lshl_add_u64 v[10:11], v[6:7], 0, v[24:25]
	v_lshl_add_u64 v[54:55], v[18:19], 0, v[28:29]
	global_load_dwordx4 v[6:9], v[10:11], off offset:256
	global_load_dwordx4 v[14:17], v[52:53], off
	s_nop 0
	global_load_dwordx4 v[10:13], v[10:11], off
	v_add_u32_e32 v210, 0, v31
	global_load_dwordx4 v[18:21], v[54:55], off
	s_movk_i32 s4, 0x180
	s_waitcnt vmcnt(0)
	v_add_u32_e32 v211, 0, v32
	v_xor_b32_e32 v215, 32, v209
	v_add_u32_e32 v201, s6, v59
	s_waitcnt vmcnt(4)
	ds_write_b128 v210, v[2:5]
	v_mul_lo_u32 v2, v22, s4
	v_bitop3_b32 v3, v24, v30, s5 bitop3:0x78
	v_lshlrev_b32_e32 v4, 4, v26
	v_add3_u32 v212, v3, v2, 0
	v_mul_lo_u32 v2, v26, s4
	v_or_b32_e32 v3, 0x100, v28
	v_and_b32_e32 v4, 0x70, v4
	v_xad_u32 v2, v3, v4, v2
	v_add_u32_e32 v214, 0, v2
	s_waitcnt vmcnt(3)
	ds_write_b128 v211, v[6:9]
	s_waitcnt vmcnt(2)
	ds_write_b128 v212, v[14:17] offset:32768
	s_waitcnt vmcnt(1)
	ds_write_b128 v212, v[10:13] offset:45056
	s_waitcnt vmcnt(0)
	ds_write_b128 v214, v[18:21] offset:32768
	s_waitcnt lgkmcnt(0)
	s_barrier
; __device__ __forceinline__ void qkt12_roll(f32x16& p0, f32x16& p1, const f32x16& negm, int kb, int qa, const bf16x8* qr) {
;   const int a0 = kb ^ (0 << 5); const bf16x8 x0 = lds_rd128<0>(a0), y0 = lds_rd128<12288>(a0);
;   const int a1 = kb ^ (1 << 5); const bf16x8 x1 = lds_rd128<0>(a1), y1 = lds_rd128<12288>(a1);
;   asm volatile("s_waitcnt lgkmcnt(2)" ::: "memory"); SBAR();
;   p0 = __builtin_amdgcn_mfma_f32_32x32x16_bf16(x0, qr[0], negm, 0, 0, 0); p1 = __builtin_amdgcn_mfma_f32_32x32x16_bf16(y0, qr[0], negm, 0, 0, 0);
;   const int a2 = kb ^ (2 << 5); const bf16x8 x2 = lds_rd128<0>(a2), y2 = lds_rd128<12288>(a2);
;   asm volatile("s_waitcnt lgkmcnt(2)" ::: "memory"); SBAR();
;   p0 = __builtin_amdgcn_mfma_f32_32x32x16_bf16(x1, qr[1], p0, 0, 0, 0); p1 = __builtin_amdgcn_mfma_f32_32x32x16_bf16(y1, qr[1], p1, 0, 0, 0);
;   const int a3 = kb ^ (3 << 5); const bf16x8 x3 = lds_rd128<0>(a3), y3 = lds_rd128<12288>(a3);
;   asm volatile("s_waitcnt lgkmcnt(2)" ::: "memory"); SBAR();
;   p0 = __builtin_amdgcn_mfma_f32_32x32x16_bf16(x2, qr[2], p0, 0, 0, 0); p1 = __builtin_amdgcn_mfma_f32_32x32x16_bf16(y2, qr[2], p1, 0, 0, 0);
;   const int a4 = kb ^ (0 << 5); const bf16x8 x4 = lds_rd128<128>(a4), y4 = lds_rd128<12416>(a4);
;   asm volatile("s_waitcnt lgkmcnt(2)" ::: "memory"); SBAR();
;   p0 = __builtin_amdgcn_mfma_f32_32x32x16_bf16(x3, qr[3], p0, 0, 0, 0); p1 = __builtin_amdgcn_mfma_f32_32x32x16_bf16(y3, qr[3], p1, 0, 0, 0);
;   const int a5 = kb ^ (1 << 5); const bf16x8 x5 = lds_rd128<128>(a5), y5 = lds_rd128<12416>(a5);
;   asm volatile("s_waitcnt lgkmcnt(2)" ::: "memory"); SBAR();
;   p0 = __builtin_amdgcn_mfma_f32_32x32x16_bf16(x4, qr[4], p0, 0, 0, 0); p1 = __builtin_amdgcn_mfma_f32_32x32x16_bf16(y4, qr[4], p1, 0, 0, 0);
;   const int a6 = kb ^ (2 << 5); const bf16x8 x6 = lds_rd128<128>(a6), y6 = lds_rd128<12416>(a6);
;   asm volatile("s_waitcnt lgkmcnt(2)" ::: "memory"); SBAR();
;   p0 = __builtin_amdgcn_mfma_f32_32x32x16_bf16(x5, qr[5], p0, 0, 0, 0); p1 = __builtin_amdgcn_mfma_f32_32x32x16_bf16(y5, qr[5], p1, 0, 0, 0);
;   const int a7 = kb ^ (3 << 5); const bf16x8 x7 = lds_rd128<128>(a7), y7 = lds_rd128<12416>(a7);
;   asm volatile("s_waitcnt lgkmcnt(2)" ::: "memory"); SBAR();
;   p0 = __builtin_amdgcn_mfma_f32_32x32x16_bf16(x6, qr[6], p0, 0, 0, 0); p1 = __builtin_amdgcn_mfma_f32_32x32x16_bf16(y6, qr[6], p1, 0, 0, 0);
	ds_read_b128 v[2:5], v209 offset:0
	ds_read_b128 v[18:21], v209 offset:0x3000
	ds_read_b128 v[60:63], v215 offset:0
	ds_read_b128 v[64:67], v215 offset:0x3000
	s_waitcnt lgkmcnt(2)
	v_add_u32_e32 v213, 0x3000, v212
	v_mfma_f32_32x32x16_bf16 v[34:49], v[2:5], v[142:145], 0
	v_xor_b32_e32 v216, 64, v209
	ds_read_b128 v[68:71], v216 offset:0
	ds_read_b128 v[72:75], v216 offset:0x3000
	s_mov_b32 s13, s12
	s_waitcnt lgkmcnt(2)
	s_mov_b32 s14, s12
	s_mov_b32 s15, s12
	v_mfma_f32_32x32x16_bf16 v[18:33], v[18:21], v[142:145], 0
	s_mov_b32 s16, s12
	s_mov_b32 s17, s12
	s_mov_b32 s18, s12
	s_mov_b32 s19, s12
	s_mov_b32 s20, s12
	s_mov_b32 s21, s12
	s_mov_b32 s22, s12
	s_mov_b32 s23, s12
	s_mov_b32 s24, s12
	s_mov_b32 s25, s12
	s_mov_b32 s26, s12
	s_mov_b32 s27, s12
	v_mov_b64_e32 v[2:3], s[12:13]
	v_mov_b64_e32 v[4:5], s[14:15]
	v_mov_b64_e32 v[6:7], s[16:17]
	v_mov_b64_e32 v[8:9], s[18:19]
	v_mov_b64_e32 v[10:11], s[20:21]
	v_mov_b64_e32 v[12:13], s[22:23]
	v_mov_b64_e32 v[14:15], s[24:25]
	v_mov_b64_e32 v[16:17], s[26:27]
	v_mfma_f32_32x32x16_bf16 v[34:49], v[60:63], v[138:141], v[34:49]
	v_xor_b32_e32 v217, 0x60, v209
	ds_read_b128 v[60:63], v217 offset:0
	v_mfma_f32_32x32x16_bf16 v[18:33], v[64:67], v[138:141], v[18:33]
	ds_read_b128 v[64:67], v217 offset:0x3000
	s_waitcnt lgkmcnt(2)
	v_mfma_f32_32x32x16_bf16 v[34:49], v[68:71], v[134:137], v[34:49]
	ds_read_b128 v[68:71], v209 offset:0x80
	v_mfma_f32_32x32x16_bf16 v[18:33], v[72:75], v[134:137], v[18:33]
	ds_read_b128 v[72:75], v209 offset:0x3080
	s_waitcnt lgkmcnt(2)
	v_mfma_f32_32x32x16_bf16 v[34:49], v[60:63], v[130:133], v[34:49]
	ds_read_b128 v[60:63], v215 offset:0x80
	v_mfma_f32_32x32x16_bf16 v[18:33], v[64:67], v[130:133], v[18:33]
	ds_read_b128 v[64:67], v215 offset:0x3080
	s_waitcnt lgkmcnt(2)
	v_mfma_f32_32x32x16_bf16 v[34:49], v[68:71], v[126:129], v[34:49]
	ds_read_b128 v[68:71], v216 offset:0x80
	v_mfma_f32_32x32x16_bf16 v[18:33], v[72:75], v[126:129], v[18:33]
	ds_read_b128 v[72:75], v216 offset:0x3080
	s_waitcnt lgkmcnt(2)
	v_mfma_f32_32x32x16_bf16 v[34:49], v[60:63], v[122:125], v[34:49]
	ds_read_b128 v[60:63], v217 offset:0x80
	v_mfma_f32_32x32x16_bf16 v[18:33], v[64:67], v[122:125], v[18:33]
	ds_read_b128 v[64:67], v217 offset:0x3080
	s_waitcnt lgkmcnt(2)
	v_mfma_f32_32x32x16_bf16 v[34:49], v[68:71], v[118:121], v[34:49]
	ds_read_b128 v[68:71], v209 offset:0x100
	v_mfma_f32_32x32x16_bf16 v[18:33], v[72:75], v[118:121], v[18:33]
	ds_read_b128 v[72:75], v209 offset:0x3100
	ds_read_b128 v[76:79], v199 offset:0
	s_waitcnt lgkmcnt(3)
	v_mfma_f32_32x32x16_bf16 v[34:49], v[60:63], v[114:117], v[34:49]
	ds_read_b128 v[60:63], v215 offset:0x100
	v_mfma_f32_32x32x16_bf16 v[18:33], v[64:67], v[114:117], v[18:33]
	ds_read_b128 v[64:67], v215 offset:0x3100
	ds_read_b128 v[80:83], v199 offset:0x400
	s_waitcnt lgkmcnt(3)
	v_mfma_f32_32x32x16_bf16 v[34:49], v[68:71], v[76:79], v[34:49]
	ds_read_b128 v[68:71], v216 offset:0x100
	v_mfma_f32_32x32x16_bf16 v[18:33], v[72:75], v[76:79], v[18:33]
	ds_read_b128 v[72:75], v216 offset:0x3100
	ds_read_b128 v[76:79], v199 offset:0x800
	s_waitcnt lgkmcnt(3)
	v_mfma_f32_32x32x16_bf16 v[34:49], v[60:63], v[80:83], v[34:49]
	ds_read_b128 v[60:63], v217 offset:0x100
	v_mfma_f32_32x32x16_bf16 v[18:33], v[64:67], v[80:83], v[18:33]
	ds_read_b128 v[64:67], v217 offset:0x3100
	ds_read_b128 v[80:83], v199 offset:0xc00
	s_waitcnt lgkmcnt(3)
	v_mfma_f32_32x32x16_bf16 v[34:49], v[68:71], v[76:79], v[34:49]
	s_waitcnt lgkmcnt(0)
; #define SWAIT() do { if constexpr (SDEPTH == 2) { if constexpr (NDQ == 4) asm volatile("s_waitcnt vmcnt(3)" ::: "memory"); else if constexpr (NDQ == 8) asm volatile("s_waitcnt vmcnt(4)" ::: "memory"); else asm volatile("s_waitcnt vmcnt(5)" ::: "memory"); } \
;     else asm volatile("s_waitcnt vmcnt(0)" ::: "memory"); } while (0)
; template <bool FIRST>
; __device__ __forceinline__ void partialSM(f32x16& p0, f32x16& p1, float& mC, float& alpha) {
;   float mx_[4] = {p0[0], p0[1], p0[2], p0[3]};
; #pragma unroll
;   for (int r = 4; r < 16; ++r) mx_[r & 3] = fmaxf(mx_[r & 3], p0[r]);
; #pragma unroll
;   for (int r = 0; r < 16; ++r) mx_[r & 3] = fmaxf(mx_[r & 3], p1[r]);
;   float pmax = fmaxf(fmaxf(mx_[0], mx_[1]), fmaxf(mx_[2], mx_[3]));
;   { auto rr = __builtin_amdgcn_permlane32_swap(__float_as_uint(pmax), __float_as_uint(pmax), false, false);
;     pmax = fmaxf(__uint_as_float(rr[0]), __uint_as_float(rr[1])); }
;   if (!FIRST && __builtin_expect(__all(pmax <= THR2), 1)) { alpha = 1.f; }
;   else { const float delta = FIRST ? fmaxf(pmax, -200.f) : fmaxf(pmax, 0.f); alpha = FIRST ? 1.f : __builtin_amdgcn_exp2f(-delta); mC += delta;
; #pragma unroll
;     for (int r = 0; r < 16; ++r) p0[r] -= delta;
; #pragma unroll
;     for (int r = 0; r < 16; ++r) p1[r] -= delta; }
; #pragma unroll
;   for (int r = 0; r < 16; ++r) p0[r] = __builtin_amdgcn_exp2f(p0[r]);
; }
;     ...
;   f32x16 pA0, pA1, pB0, pB1; float alA, alB; bf16x8 pa0, pa1, pa2, pa3; const int NT = nkeys / KVBLK;
;   const int kb0 = (int)(uintptr_t)K_lds + r32 * ROWB + (((r32 & SWM) << 4) ^ (hi << 4));
;   const int qa0 = (int)(uintptr_t)qls;
;     ...
;   constexpr int SE = 0, SO = SDEPTH - 1;
;   SLOAD(SE, kbeg); asm volatile("s_waitcnt vmcnt(0)" ::: "memory"); SWRITE(0, SE); __syncthreads();
;   constexpr bool SLICED = (NDQ == 8 && NQL == 0 && BIAS == 1);
;   NEGM_UPD(kbeg); QKT(pA0, pA1, 0); BIASADD(pA0, pA1, kbeg); partialSM<true>(pA0, pA1, mC, alA);
;   if constexpr (SLICED) {
; #pragma unroll
;     for (int r = 0; r < 16; ++r) pA1[r] = __builtin_amdgcn_exp2f(pA1[r]); }
;   SLOAD(SO, kbeg + KVBLK); if constexpr (SDEPTH == 2) { if (2 < NT) SLOAD(SE, kbeg + 2 * KVBLK); }
;   SWAIT(); SWRITE(1, SO); __syncthreads();
	v_mfma_f32_32x32x16_bf16 v[18:33], v[72:75], v[76:79], v[18:33]
	v_mfma_f32_32x32x16_bf16 v[34:49], v[60:63], v[80:83], v[34:49]
	v_mfma_f32_32x32x16_bf16 v[18:33], v[64:67], v[80:83], v[18:33]
	s_mov_b64 s[4:5], 0x20000
	v_lshl_add_u64 v[60:61], v[52:53], 0, s[4:5]
	s_mov_b64 s[4:5], 0x30000
	v_lshl_add_u64 v[64:65], v[52:53], 0, s[4:5]
	s_mov_b32 s4, 0x20000
	global_load_dwordx4 v[60:63], v[60:61], off offset:256
	s_nop 0
	global_load_dwordx4 v[82:85], v[64:65], off offset:256
	v_add_co_u32_e32 v64, vcc, s4, v52
	s_mov_b32 s4, 0x30000
	s_nop 0
	v_addc_co_u32_e32 v65, vcc, 0, v53, vcc
	v_add_co_u32_e32 v52, vcc, s4, v52
	s_movk_i32 s4, 0x2000
	s_nop 0
	v_addc_co_u32_e32 v53, vcc, 0, v53, vcc
	global_load_dwordx4 v[86:89], v[64:65], off
	global_load_dwordx4 v[90:93], v[52:53], off
	v_add_co_u32_e32 v52, vcc, s4, v54
	v_max_f32_e32 v66, v38, v38
	s_nop 0
	v_addc_co_u32_e32 v53, vcc, 0, v55, vcc
	global_load_dwordx4 v[52:55], v[52:53], off
	v_max_f32_e32 v67, v34, v34
	v_max_f32_e32 v64, v67, v66
	v_max_f32_e32 v65, v39, v39
	v_max_f32_e32 v66, v35, v35
	v_max_f32_e32 v65, v66, v65
	v_max_f32_e32 v66, v41, v41
	v_max_f32_e32 v67, v37, v37
	v_max_f32_e32 v66, v67, v66
	v_max3_f32 v67, v36, v40, v44
	v_max3_f32 v66, v66, v45, v49
	v_max3_f32 v64, v64, v42, v46
	v_max3_f32 v65, v65, v43, v47
	v_max3_f32 v67, v67, v48, v20
	v_max3_f32 v66, v66, v21, v25
	v_max3_f32 v64, v64, v18, v22
	v_max3_f32 v65, v65, v19, v23
	v_max3_f32 v67, v67, v24, v28
	v_max3_f32 v66, v66, v29, v33
	v_max3_f32 v64, v64, v26, v30
	v_max3_f32 v65, v65, v27, v31
	v_max3_f32 v66, v67, v32, v66
	v_max3_f32 v64, v64, v65, v66
	v_mov_b32_e32 v65, v64
	s_nop 1
	v_permlane32_swap_b32_e32 v64, v65
	s_mov_b32 s4, 0xc3480000
	v_max3_f32 v64, v64, v65, s4
	v_sub_f32_e32 v34, v34, v64
	v_sub_f32_e32 v35, v35, v64
	v_sub_f32_e32 v36, v36, v64
	v_sub_f32_e32 v37, v37, v64
	v_sub_f32_e32 v38, v38, v64
	v_sub_f32_e32 v39, v39, v64
	v_sub_f32_e32 v40, v40, v64
	v_sub_f32_e32 v41, v41, v64
	v_sub_f32_e32 v42, v42, v64
	v_sub_f32_e32 v43, v43, v64
	v_sub_f32_e32 v44, v44, v64
	v_sub_f32_e32 v45, v45, v64
	v_sub_f32_e32 v46, v46, v64
	v_sub_f32_e32 v47, v47, v64
	v_sub_f32_e32 v48, v48, v64
	v_sub_f32_e32 v49, v49, v64
	v_sub_f32_e32 v66, v18, v64
	v_exp_f32_e32 v146, v34
	v_exp_f32_e32 v161, v35
	v_exp_f32_e32 v147, v36
	v_exp_f32_e32 v160, v37
	v_exp_f32_e32 v148, v38
	v_exp_f32_e32 v159, v39
	v_exp_f32_e32 v149, v40
	v_exp_f32_e32 v158, v41
	v_exp_f32_e32 v150, v42
	v_exp_f32_e32 v157, v43
	v_exp_f32_e32 v151, v44
	v_exp_f32_e32 v156, v45
	v_exp_f32_e32 v152, v46
	v_exp_f32_e32 v155, v47
	v_exp_f32_e32 v153, v48
	v_exp_f32_e32 v154, v49
	v_and_b32_e32 v18, 15, v56
	v_sub_f32_e32 v67, v19, v64
	s_waitcnt vmcnt(0)
	s_addk_i32 s6, 0x4000
	v_or_b32_e32 v50, s59, v50
	v_lshlrev_b32_e32 v18, 4, v18
	v_mov_b32_e32 v19, v1
	v_add_f32_e32 v226, 0, v64
	v_sub_f32_e32 v81, v33, v64
	v_sub_f32_e32 v80, v32, v64
	v_sub_f32_e32 v79, v31, v64
	v_sub_f32_e32 v78, v30, v64
	v_sub_f32_e32 v77, v29, v64
	v_sub_f32_e32 v76, v28, v64
	v_sub_f32_e32 v75, v27, v64
	v_sub_f32_e32 v74, v26, v64
	v_sub_f32_e32 v73, v25, v64
	v_sub_f32_e32 v72, v24, v64
	v_sub_f32_e32 v71, v23, v64
	v_sub_f32_e32 v70, v22, v64
	v_sub_f32_e32 v69, v21, v64
	v_sub_f32_e32 v68, v20, v64
	s_waitcnt vmcnt(4)
	ds_write_b128 v210, v[60:63] offset:16384
	s_waitcnt vmcnt(3)
	ds_write_b128 v211, v[82:85] offset:16384
	s_waitcnt vmcnt(2)
	ds_write_b128 v212, v[86:89] offset:57344
	s_waitcnt vmcnt(1)
	ds_write_b128 v213, v[90:93] offset:57344
	s_waitcnt vmcnt(0)
	ds_write_b128 v214, v[52:55] offset:57344
	v_add_u32_e32 v221, 0x6000, v209
	v_cmp_gt_u32_e64 s[4:5], 32, v57
	v_add_u32_e32 v208, s6, v59
	v_lshl_add_u64 v[188:189], v[50:51], 0, v[18:19]
	v_lshl_or_b32 v186, v58, 4, v186
	v_mov_b32_e32 v229, 0
	v_mov_b64_e32 v[64:65], v[16:17]
	v_mov_b64_e32 v[48:49], v[16:17]
	v_mov_b64_e32 v[32:33], v[16:17]
	v_xor_b32_e32 v220, 32, v221
	v_xor_b32_e32 v219, 64, v221
	v_xor_b32_e32 v218, 0x60, v221
	v_lshl_add_u32 v200, v0, 2, v183
	v_add_u32_e32 v185, v183, v184
	v_mov_b32_e32 v222, 1.0
	v_mov_b64_e32 v[62:63], v[14:15]
	v_mov_b64_e32 v[60:61], v[12:13]
	v_mov_b64_e32 v[58:59], v[10:11]
	v_mov_b64_e32 v[56:57], v[8:9]
	v_mov_b64_e32 v[54:55], v[6:7]
	v_mov_b64_e32 v[52:53], v[4:5]
	v_mov_b64_e32 v[50:51], v[2:3]
	v_mov_b64_e32 v[46:47], v[14:15]
	v_mov_b64_e32 v[44:45], v[12:13]
	v_mov_b64_e32 v[42:43], v[10:11]
	v_mov_b64_e32 v[40:41], v[8:9]
	v_mov_b64_e32 v[38:39], v[6:7]
	v_mov_b64_e32 v[36:37], v[4:5]
	v_mov_b64_e32 v[34:35], v[2:3]
	v_mov_b64_e32 v[30:31], v[14:15]
	v_mov_b64_e32 v[28:29], v[12:13]
	v_mov_b64_e32 v[26:27], v[10:11]
	v_mov_b64_e32 v[24:25], v[8:9]
	v_mov_b64_e32 v[22:23], v[6:7]
	v_mov_b64_e32 v[20:21], v[4:5]
	v_mov_b64_e32 v[18:19], v[2:3]
	v_mov_b32_e32 v207, 0
	v_mov_b32_e32 v82, 0
	v_mov_b32_e32 v83, v229
	v_mov_b32_e32 v84, v229
	v_mov_b32_e32 v85, v229
	v_mov_b32_e32 v86, v229
	v_mov_b32_e32 v87, v229
	v_mov_b32_e32 v88, v229
	v_mov_b32_e32 v89, v229
	v_mov_b32_e32 v90, v229
	v_mov_b32_e32 v91, v229
	v_mov_b32_e32 v92, v229
	v_mov_b32_e32 v93, v229
	v_mov_b32_e32 v94, v229
	v_mov_b32_e32 v95, v229
	v_mov_b32_e32 v96, v229
	v_mov_b32_e32 v97, v229
	ds_read_b128 v[192:195], v199 offset:0
	ds_read_b128 v[202:205], v199 offset:0x400
	s_waitcnt lgkmcnt(0)
	s_waitcnt lgkmcnt(0)
	s_barrier

; __device__ __forceinline__ void qkt12_roll(f32x16& p0, f32x16& p1, const f32x16& negm, int kb, int qa, const bf16x8* qr) {
;   const int a0 = kb ^ (0 << 5); const bf16x8 x0 = lds_rd128<0>(a0), y0 = lds_rd128<12288>(a0);
;   const int a1 = kb ^ (1 << 5); const bf16x8 x1 = lds_rd128<0>(a1), y1 = lds_rd128<12288>(a1);
;   asm volatile("s_waitcnt lgkmcnt(2)" ::: "memory"); SBAR();
;   p0 = __builtin_amdgcn_mfma_f32_32x32x16_bf16(x0, qr[0], negm, 0, 0, 0); p1 = __builtin_amdgcn_mfma_f32_32x32x16_bf16(y0, qr[0], negm, 0, 0, 0);
;   const int a2 = kb ^ (2 << 5); const bf16x8 x2 = lds_rd128<0>(a2), y2 = lds_rd128<12288>(a2);
;   asm volatile("s_waitcnt lgkmcnt(2)" ::: "memory"); SBAR();
;   p0 = __builtin_amdgcn_mfma_f32_32x32x16_bf16(x1, qr[1], p0, 0, 0, 0); p1 = __builtin_amdgcn_mfma_f32_32x32x16_bf16(y1, qr[1], p1, 0, 0, 0);
;   const int a3 = kb ^ (3 << 5); const bf16x8 x3 = lds_rd128<0>(a3), y3 = lds_rd128<12288>(a3);
;   asm volatile("s_waitcnt lgkmcnt(2)" ::: "memory"); SBAR();
;   p0 = __builtin_amdgcn_mfma_f32_32x32x16_bf16(x2, qr[2], p0, 0, 0, 0); p1 = __builtin_amdgcn_mfma_f32_32x32x16_bf16(y2, qr[2], p1, 0, 0, 0);
;   const int a4 = kb ^ (0 << 5); const bf16x8 x4 = lds_rd128<128>(a4), y4 = lds_rd128<12416>(a4);
;   asm volatile("s_waitcnt lgkmcnt(2)" ::: "memory"); SBAR();
;   p0 = __builtin_amdgcn_mfma_f32_32x32x16_bf16(x3, qr[3], p0, 0, 0, 0); p1 = __builtin_amdgcn_mfma_f32_32x32x16_bf16(y3, qr[3], p1, 0, 0, 0);
;   const int a5 = kb ^ (1 << 5); const bf16x8 x5 = lds_rd128<128>(a5), y5 = lds_rd128<12416>(a5);
;   asm volatile("s_waitcnt lgkmcnt(2)" ::: "memory"); SBAR();
;   p0 = __builtin_amdgcn_mfma_f32_32x32x16_bf16(x4, qr[4], p0, 0, 0, 0); p1 = __builtin_amdgcn_mfma_f32_32x32x16_bf16(y4, qr[4], p1, 0, 0, 0);
;   const int a6 = kb ^ (2 << 5); const bf16x8 x6 = lds_rd128<128>(a6), y6 = lds_rd128<12416>(a6);
;   asm volatile("s_waitcnt lgkmcnt(2)" ::: "memory"); SBAR();
;   p0 = __builtin_amdgcn_mfma_f32_32x32x16_bf16(x5, qr[5], p0, 0, 0, 0); p1 = __builtin_amdgcn_mfma_f32_32x32x16_bf16(y5, qr[5], p1, 0, 0, 0);
;   const int a7 = kb ^ (3 << 5); const bf16x8 x7 = lds_rd128<128>(a7), y7 = lds_rd128<12416>(a7);
;   asm volatile("s_waitcnt lgkmcnt(2)" ::: "memory"); SBAR();
;   p0 = __builtin_amdgcn_mfma_f32_32x32x16_bf16(x6, qr[6], p0, 0, 0, 0); p1 = __builtin_amdgcn_mfma_f32_32x32x16_bf16(y6, qr[6], p1, 0, 0, 0);
.Lmy_negm_back_0:
	ds_read_b128 v[82:85], v221 offset:0
	ds_read_b128 v[162:165], v221 offset:0x3000
	ds_read_b128 v[166:169], v220 offset:0
	ds_read_b128 v[170:173], v220 offset:0x3000
	s_waitcnt lgkmcnt(2)
	s_nop 1
	v_mfma_f32_32x32x16_bf16 v[98:113], v[82:85], v[142:145], v[66:81]
	v_mfma_f32_32x32x16_bf16 v[82:97], v[162:165], v[142:145], v[66:81]
	ds_read_b128 v[162:165], v219 offset:0
	ds_read_b128 v[174:177], v219 offset:0x3000
	s_waitcnt lgkmcnt(2)
	v_mfma_f32_32x32x16_bf16 v[98:113], v[166:169], v[138:141], v[98:113]
	ds_read_b128 v[166:169], v218 offset:0
	v_mfma_f32_32x32x16_bf16 v[82:97], v[170:173], v[138:141], v[82:97]
	ds_read_b128 v[170:173], v218 offset:0x3000
	s_waitcnt lgkmcnt(2)
	v_mfma_f32_32x32x16_bf16 v[98:113], v[162:165], v[134:137], v[98:113]
	ds_read_b128 v[162:165], v221 offset:0x80
	v_mfma_f32_32x32x16_bf16 v[82:97], v[174:177], v[134:137], v[82:97]
	ds_read_b128 v[174:177], v221 offset:0x3080
	s_waitcnt lgkmcnt(2)
	v_mfma_f32_32x32x16_bf16 v[98:113], v[166:169], v[130:133], v[98:113]
	ds_read_b128 v[166:169], v220 offset:0x80
	v_mfma_f32_32x32x16_bf16 v[82:97], v[170:173], v[130:133], v[82:97]
	ds_read_b128 v[170:173], v220 offset:0x3080
	s_waitcnt lgkmcnt(2)
	v_mfma_f32_32x32x16_bf16 v[98:113], v[162:165], v[126:129], v[98:113]
	ds_read_b128 v[162:165], v219 offset:0x80
	v_mfma_f32_32x32x16_bf16 v[82:97], v[174:177], v[126:129], v[82:97]
	ds_read_b128 v[174:177], v219 offset:0x3080
	s_waitcnt lgkmcnt(2)
	v_mfma_f32_32x32x16_bf16 v[98:113], v[166:169], v[122:125], v[98:113]
	ds_read_b128 v[166:169], v218 offset:0x80
	v_mfma_f32_32x32x16_bf16 v[82:97], v[170:173], v[122:125], v[82:97]
	ds_read_b128 v[170:173], v218 offset:0x3080
	s_waitcnt lgkmcnt(2)
	v_mfma_f32_32x32x16_bf16 v[98:113], v[162:165], v[118:121], v[98:113]
	ds_read_b128 v[162:165], v221 offset:0x100
	v_mfma_f32_32x32x16_bf16 v[82:97], v[174:177], v[118:121], v[82:97]
	ds_read_b128 v[174:177], v221 offset:0x3100
	s_waitcnt lgkmcnt(2)
	v_mfma_f32_32x32x16_bf16 v[98:113], v[166:169], v[114:117], v[98:113]
	ds_read_b128 v[166:169], v220 offset:0x100
	v_mfma_f32_32x32x16_bf16 v[82:97], v[170:173], v[114:117], v[82:97]
	ds_read_b128 v[170:173], v220 offset:0x3100
	s_waitcnt lgkmcnt(2)
	v_mfma_f32_32x32x16_bf16 v[98:113], v[162:165], v[192:195], v[98:113]
	ds_read_b128 v[162:165], v219 offset:0x100
	v_mfma_f32_32x32x16_bf16 v[82:97], v[174:177], v[192:195], v[82:97]
	ds_read_b128 v[174:177], v219 offset:0x3100
	ds_read_b128 v[178:181], v199 offset:0x800
	s_waitcnt lgkmcnt(3)
	v_mfma_f32_32x32x16_bf16 v[98:113], v[166:169], v[202:205], v[98:113]
	ds_read_b128 v[166:169], v218 offset:0x100
	v_mfma_f32_32x32x16_bf16 v[82:97], v[170:173], v[202:205], v[82:97]
	ds_read_b128 v[170:173], v218 offset:0x3100
	ds_read_b128 v[230:233], v199 offset:0xc00
	s_waitcnt lgkmcnt(3)
	v_mfma_f32_32x32x16_bf16 v[98:113], v[162:165], v[178:181], v[98:113]
	s_waitcnt lgkmcnt(0)
	v_mfma_f32_32x32x16_bf16 v[82:97], v[174:177], v[178:181], v[82:97]
	v_mfma_f32_32x32x16_bf16 v[98:113], v[166:169], v[230:233], v[98:113]
	v_mfma_f32_32x32x16_bf16 v[82:97], v[170:173], v[230:233], v[82:97]
	s_nop 10
	v_max_f32_e32 v162, v98, v102
	v_max_f32_e32 v163, v99, v103
	v_max_f32_e32 v164, v101, v105
	v_max3_f32 v165, v100, v104, v108
	v_max3_f32 v164, v164, v109, v113
	v_max3_f32 v162, v162, v106, v110
	v_max3_f32 v163, v163, v107, v111
	v_max3_f32 v165, v165, v112, v84
	v_max3_f32 v164, v164, v85, v89
	v_max3_f32 v162, v162, v82, v86
	v_max3_f32 v163, v163, v83, v87
	v_max3_f32 v165, v165, v88, v92
	v_max3_f32 v164, v164, v93, v97
	v_max3_f32 v162, v162, v90, v94
	v_max3_f32 v163, v163, v91, v95
	v_max3_f32 v164, v165, v96, v164
	v_max3_f32 v162, v162, v163, v164
	v_cmp_ge_f32_e32 vcc, s48, v162
	s_cmp_eq_u64 vcc, exec
	s_cbranch_scc0 .LBB0_374
	v_mov_b32_e32 v228, v226
	v_mov_b32_e32 v227, 1.0

; __device__ __forceinline__ void qkt12_roll(f32x16& p0, f32x16& p1, const f32x16& negm, int kb, int qa, const bf16x8* qr) {
;   const int a0 = kb ^ (0 << 5); const bf16x8 x0 = lds_rd128<0>(a0), y0 = lds_rd128<12288>(a0);
;   const int a1 = kb ^ (1 << 5); const bf16x8 x1 = lds_rd128<0>(a1), y1 = lds_rd128<12288>(a1);
;   asm volatile("s_waitcnt lgkmcnt(2)" ::: "memory"); SBAR();
;   p0 = __builtin_amdgcn_mfma_f32_32x32x16_bf16(x0, qr[0], negm, 0, 0, 0); p1 = __builtin_amdgcn_mfma_f32_32x32x16_bf16(y0, qr[0], negm, 0, 0, 0);
;   const int a2 = kb ^ (2 << 5); const bf16x8 x2 = lds_rd128<0>(a2), y2 = lds_rd128<12288>(a2);
;   asm volatile("s_waitcnt lgkmcnt(2)" ::: "memory"); SBAR();
;   p0 = __builtin_amdgcn_mfma_f32_32x32x16_bf16(x1, qr[1], p0, 0, 0, 0); p1 = __builtin_amdgcn_mfma_f32_32x32x16_bf16(y1, qr[1], p1, 0, 0, 0);
;   const int a3 = kb ^ (3 << 5); const bf16x8 x3 = lds_rd128<0>(a3), y3 = lds_rd128<12288>(a3);
;   asm volatile("s_waitcnt lgkmcnt(2)" ::: "memory"); SBAR();
;   p0 = __builtin_amdgcn_mfma_f32_32x32x16_bf16(x2, qr[2], p0, 0, 0, 0); p1 = __builtin_amdgcn_mfma_f32_32x32x16_bf16(y2, qr[2], p1, 0, 0, 0);
;   const int a4 = kb ^ (0 << 5); const bf16x8 x4 = lds_rd128<128>(a4), y4 = lds_rd128<12416>(a4);
;   asm volatile("s_waitcnt lgkmcnt(2)" ::: "memory"); SBAR();
;   p0 = __builtin_amdgcn_mfma_f32_32x32x16_bf16(x3, qr[3], p0, 0, 0, 0); p1 = __builtin_amdgcn_mfma_f32_32x32x16_bf16(y3, qr[3], p1, 0, 0, 0);
;   const int a5 = kb ^ (1 << 5); const bf16x8 x5 = lds_rd128<128>(a5), y5 = lds_rd128<12416>(a5);
;   asm volatile("s_waitcnt lgkmcnt(2)" ::: "memory"); SBAR();
;   p0 = __builtin_amdgcn_mfma_f32_32x32x16_bf16(x4, qr[4], p0, 0, 0, 0); p1 = __builtin_amdgcn_mfma_f32_32x32x16_bf16(y4, qr[4], p1, 0, 0, 0);
;   const int a6 = kb ^ (2 << 5); const bf16x8 x6 = lds_rd128<128>(a6), y6 = lds_rd128<12416>(a6);
;   asm volatile("s_waitcnt lgkmcnt(2)" ::: "memory"); SBAR();
;   p0 = __builtin_amdgcn_mfma_f32_32x32x16_bf16(x5, qr[5], p0, 0, 0, 0); p1 = __builtin_amdgcn_mfma_f32_32x32x16_bf16(y5, qr[5], p1, 0, 0, 0);
;   const int a7 = kb ^ (3 << 5); const bf16x8 x7 = lds_rd128<128>(a7), y7 = lds_rd128<12416>(a7);
;   asm volatile("s_waitcnt lgkmcnt(2)" ::: "memory"); SBAR();
;   p0 = __builtin_amdgcn_mfma_f32_32x32x16_bf16(x6, qr[6], p0, 0, 0, 0); p1 = __builtin_amdgcn_mfma_f32_32x32x16_bf16(y6, qr[6], p1, 0, 0, 0);
.Lmy_negm_back_1:
	ds_read_b128 v[66:69], v209 offset:0
	ds_read_b128 v[162:165], v209 offset:0x3000
	ds_read_b128 v[166:169], v215 offset:0
	ds_read_b128 v[170:173], v215 offset:0x3000
	s_waitcnt lgkmcnt(2)
	s_nop 1
	v_mfma_f32_32x32x16_bf16 v[98:113], v[66:69], v[142:145], v[82:97]
	v_mfma_f32_32x32x16_bf16 v[66:81], v[162:165], v[142:145], v[82:97]
	ds_read_b128 v[162:165], v216 offset:0
	ds_read_b128 v[174:177], v216 offset:0x3000
	s_waitcnt lgkmcnt(2)
	v_mfma_f32_32x32x16_bf16 v[98:113], v[166:169], v[138:141], v[98:113]
	ds_read_b128 v[166:169], v217 offset:0
	v_mfma_f32_32x32x16_bf16 v[66:81], v[170:173], v[138:141], v[66:81]
	ds_read_b128 v[170:173], v217 offset:0x3000
	s_waitcnt lgkmcnt(2)
	v_mfma_f32_32x32x16_bf16 v[98:113], v[162:165], v[134:137], v[98:113]
	ds_read_b128 v[162:165], v209 offset:0x80
	v_mfma_f32_32x32x16_bf16 v[66:81], v[174:177], v[134:137], v[66:81]
	ds_read_b128 v[174:177], v209 offset:0x3080
	s_waitcnt lgkmcnt(2)
	v_mfma_f32_32x32x16_bf16 v[98:113], v[166:169], v[130:133], v[98:113]
	ds_read_b128 v[166:169], v215 offset:0x80
	v_mfma_f32_32x32x16_bf16 v[66:81], v[170:173], v[130:133], v[66:81]
	ds_read_b128 v[170:173], v215 offset:0x3080
	s_waitcnt lgkmcnt(2)
	v_mfma_f32_32x32x16_bf16 v[98:113], v[162:165], v[126:129], v[98:113]
	ds_read_b128 v[162:165], v216 offset:0x80
	v_mfma_f32_32x32x16_bf16 v[66:81], v[174:177], v[126:129], v[66:81]
	ds_read_b128 v[174:177], v216 offset:0x3080
	s_waitcnt lgkmcnt(2)
	v_mfma_f32_32x32x16_bf16 v[98:113], v[166:169], v[122:125], v[98:113]
	ds_read_b128 v[166:169], v217 offset:0x80
	v_mfma_f32_32x32x16_bf16 v[66:81], v[170:173], v[122:125], v[66:81]
	ds_read_b128 v[170:173], v217 offset:0x3080
	s_waitcnt lgkmcnt(2)
	v_mfma_f32_32x32x16_bf16 v[98:113], v[162:165], v[118:121], v[98:113]
	ds_read_b128 v[162:165], v209 offset:0x100
	v_mfma_f32_32x32x16_bf16 v[66:81], v[174:177], v[118:121], v[66:81]
	ds_read_b128 v[174:177], v209 offset:0x3100
	s_waitcnt lgkmcnt(2)
	v_mfma_f32_32x32x16_bf16 v[98:113], v[166:169], v[114:117], v[98:113]
	ds_read_b128 v[166:169], v215 offset:0x100
	v_mfma_f32_32x32x16_bf16 v[66:81], v[170:173], v[114:117], v[66:81]
	ds_read_b128 v[170:173], v215 offset:0x3100
	s_waitcnt lgkmcnt(2)
	v_mfma_f32_32x32x16_bf16 v[98:113], v[162:165], v[192:195], v[98:113]
	ds_read_b128 v[162:165], v216 offset:0x100
	v_mfma_f32_32x32x16_bf16 v[66:81], v[174:177], v[192:195], v[66:81]
	ds_read_b128 v[174:177], v216 offset:0x3100
	ds_read_b128 v[178:181], v199 offset:0x800
	s_waitcnt lgkmcnt(3)
	v_mfma_f32_32x32x16_bf16 v[98:113], v[166:169], v[202:205], v[98:113]
	ds_read_b128 v[166:169], v217 offset:0x100
	v_mfma_f32_32x32x16_bf16 v[66:81], v[170:173], v[202:205], v[66:81]
	ds_read_b128 v[170:173], v217 offset:0x3100
	ds_read_b128 v[232:235], v199 offset:0xc00
	s_waitcnt lgkmcnt(3)
	v_mfma_f32_32x32x16_bf16 v[98:113], v[162:165], v[178:181], v[98:113]
	s_waitcnt lgkmcnt(0)
	v_mfma_f32_32x32x16_bf16 v[66:81], v[174:177], v[178:181], v[66:81]
	v_mfma_f32_32x32x16_bf16 v[98:113], v[166:169], v[232:235], v[98:113]
	v_mfma_f32_32x32x16_bf16 v[66:81], v[170:173], v[232:235], v[66:81]
	s_nop 10
	v_max_f32_e32 v162, v98, v102
	v_max_f32_e32 v163, v99, v103
	v_max_f32_e32 v164, v101, v105
	v_max3_f32 v165, v100, v104, v108
	v_max3_f32 v164, v164, v109, v113
	v_max3_f32 v162, v162, v106, v110
	v_max3_f32 v163, v163, v107, v111
	v_max3_f32 v165, v165, v112, v68
	v_max3_f32 v164, v164, v69, v73
	v_max3_f32 v162, v162, v66, v70
	v_max3_f32 v163, v163, v67, v71
	v_max3_f32 v165, v165, v72, v76
	v_max3_f32 v164, v164, v77, v81
	v_max3_f32 v162, v162, v74, v78
	v_max3_f32 v163, v163, v75, v79
	v_max3_f32 v164, v165, v80, v164
	v_max3_f32 v162, v162, v163, v164
	v_cmp_ge_f32_e32 vcc, s48, v162
	s_cmp_eq_u64 vcc, exec
	v_mov_b32_e32 v223, 1.0
	s_cbranch_scc0 .LBB0_375
	v_mov_b32_e32 v226, v228

; __device__ __forceinline__ float bf2f(unsigned short b) { return __uint_as_float(((unsigned)b) << 16); }
; __device__ __forceinline__ unsigned pk2(float lo, float hi) { return f2bf(lo) | (f2bf(hi) << 16); }
;     ...
;   const bf16_t* Qw = Qb + (long)(wid * QBLK + r32) * ldq + hi * 8;
;   char* qls = lds + LDS_Q_OFF + wid * 8192 + lane * 16;
; #pragma unroll
;   for (int d0 = 0; d0 < NDQ - NQL; ++d0) qr[d0] = *reinterpret_cast<const bf16x8*>(Qw + d0 * 16);
;   if constexpr (ROPEQ) {
;     static_assert(NDQ == 12 && NQL >= 4, "ROPEQ: MLA layout");
; #pragma unroll
;     for (int d0 = NDQ - NQL; d0 < 8; ++d0) *reinterpret_cast<bf16x8*>(qls + (d0 - (NDQ - NQL)) * 1024) = *reinterpret_cast<const bf16x8*>(Qw + d0 * 16);
;     const int qrow = q0 + wid * QBLK + r32;
; #pragma unroll
;     for (int pr = 0; pr < 2; ++pr) {
;       const bf16x8 xa = *reinterpret_cast<const bf16x8*>(Qw + (8 + pr) * 16), xb = *reinterpret_cast<const bf16x8*>(Qw + (10 + pr) * 16);
;       const float* cp = cosp + (size_t)qrow * 32 + pr * 16 + hi * 8; const float* sp = sinp + (size_t)qrow * 32 + pr * 16 + hi * 8;
;       const f32x4 c0 = *(const f32x4*)cp, c1 = *(const f32x4*)(cp + 4), s0 = *(const f32x4*)sp, s1 = *(const f32x4*)(sp + 4);
;       float ya[8], yb[8];
; #pragma unroll
;       for (int t = 0; t < 8; ++t) { const float x1 = bf2f((unsigned short)xa[t]), x2 = bf2f((unsigned short)xb[t]); const float c = t < 4 ? c0[t & 3] : c1[t & 3], sn = t < 4 ? s0[t & 3] : s1[t & 3];
;         ya[t] = x1 * c - x2 * sn; yb[t] = x2 * c + x1 * sn; }
;       u32x4 wa = {pk2(ya[0], ya[1]), pk2(ya[2], ya[3]), pk2(ya[4], ya[5]), pk2(ya[6], ya[7])}, wb = {pk2(yb[0], yb[1]), pk2(yb[2], yb[3]), pk2(yb[4], yb[5]), pk2(yb[6], yb[7])};
;       *reinterpret_cast<u32x4*>(qls + (8 + pr - (NDQ - NQL)) * 1024) = wa; *reinterpret_cast<u32x4*>(qls + (10 + pr - (NDQ - NQL)) * 1024) = wb; }
.LBB0_384:
	s_and_b64 vcc, exec, s[4:5]
	s_cbranch_vccz .LBB0_357
	v_readlane_b32 s4, v254, 21
	v_mbcnt_lo_u32_b32 v56, -1, 0
	v_mbcnt_hi_u32_b32 v56, -1, v56
	v_mov_b32_e32 v185, v1
	v_and_b32_e32 v0, 31, v56
	v_add_u32_e32 v30, s4, v56
	v_ashrrev_i32_e32 v4, 6, v30
	v_and_b32_e32 v2, 0x3fffffc0, v30
	v_lshlrev_b32_e32 v182, 5, v4
	v_bfe_u32 v198, v56, 5, 1
	v_lshl_add_u32 v183, v2, 2, s37
	v_or_b32_e32 v5, v182, v0
	v_mov_b64_e32 v[2:3], s[64:65]
	v_and_b32_e32 v57, 63, v56
	v_mad_i64_i32 v[2:3], s[4:5], v5, s1, v[2:3]
	v_lshlrev_b32_e32 v184, 4, v198
	v_lshl_add_u64 v[22:23], v[2:3], 0, v[184:185]
	v_lshlrev_b32_e32 v2, 13, v4
	v_lshlrev_b32_e32 v28, 4, v57
	v_readlane_b32 s4, v254, 58
	v_and_b32_e32 v6, 32, v56
	v_mov_b32_e32 v7, v1
	v_add3_u32 v199, s4, v2, v28
	v_or_b32_e32 v2, s58, v0
	v_add_u32_e32 v2, v2, v182
	v_ashrrev_i32_e32 v3, 31, v2
	v_lshlrev_b64 v[2:3], 7, v[2:3]
	v_lshl_add_u64 v[4:5], s[50:51], 0, v[2:3]
	v_lshl_add_u64 v[32:33], v[4:5], 0, v[6:7]
	v_lshl_add_u64 v[2:3], s[56:57], 0, v[2:3]
	s_waitcnt lgkmcnt(0)
	s_barrier
	global_load_dwordx4 v[158:161], v[22:23], off
	global_load_dwordx4 v[154:157], v[22:23], off offset:32
	global_load_dwordx4 v[150:153], v[22:23], off offset:64
	global_load_dwordx4 v[146:149], v[22:23], off offset:96
	global_load_dwordx4 v[142:145], v[22:23], off offset:128
	global_load_dwordx4 v[138:141], v[22:23], off offset:160
	global_load_dwordx4 v[134:137], v[22:23], off offset:192
	global_load_dwordx4 v[130:133], v[22:23], off offset:224
	v_lshl_add_u64 v[34:35], v[2:3], 0, v[6:7]
	global_load_dwordx4 v[2:5], v[32:33], off offset:16
	global_load_dwordx4 v[6:9], v[32:33], off
	global_load_dwordx4 v[10:13], v[34:35], off offset:16
	global_load_dwordx4 v[14:17], v[34:35], off
	global_load_dwordx4 v[18:21], v[22:23], off offset:256
	global_load_dwordx4 v[24:27], v[22:23], off offset:320
	s_cmp_lg_u32 0, -1
	s_cselect_b32 s6, 0, 0
	s_cmp_lg_u32 s44, -1
	s_cselect_b32 s4, s44, 0
	v_mov_b32_e32 v29, v1
	s_movk_i32 s5, 0x70
	s_mov_b32 s64, -1
	v_and_b32_e32 v58, 7, v56
	s_waitcnt vmcnt(4)
	v_mov_b32_e32 v40, v6
	v_mov_b32_e32 v41, v8
	s_waitcnt vmcnt(2)
	v_mov_b32_e32 v42, v14
	s_waitcnt vmcnt(1)
	v_lshlrev_b32_e32 v37, 16, v19
	v_lshlrev_b32_e32 v36, 16, v18
	s_waitcnt vmcnt(0)
	v_lshlrev_b32_e32 v39, 16, v25
	v_lshlrev_b32_e32 v38, 16, v24
	v_and_b32_e32 v19, 0xffff0000, v19
	v_and_b32_e32 v18, 0xffff0000, v18
	v_and_b32_e32 v25, 0xffff0000, v25
	v_and_b32_e32 v24, 0xffff0000, v24
	v_mov_b32_e32 v43, v16
	v_mov_b32_e32 v16, v15
	v_mov_b32_e32 v8, v7
	v_pk_mul_f32 v[6:7], v[16:17], v[18:19]
	v_pk_mul_f32 v[14:15], v[42:43], v[38:39]
	v_pk_mul_f32 v[16:17], v[16:17], v[24:25]
	v_pk_mul_f32 v[44:45], v[42:43], v[36:37]
	v_pk_fma_f32 v[6:7], v[8:9], v[24:25], v[6:7]
	v_pk_fma_f32 v[14:15], v[40:41], v[36:37], v[14:15] neg_lo:[0,0,1] neg_hi:[0,0,1]
	v_pk_fma_f32 v[8:9], v[8:9], v[18:19], v[16:17] neg_lo:[0,0,1] neg_hi:[0,0,1]
	v_lshlrev_b32_e32 v17, 16, v21
	v_lshlrev_b32_e32 v16, 16, v20
	v_and_b32_e32 v21, 0xffff0000, v21
	v_and_b32_e32 v20, 0xffff0000, v20
	v_and_b32_e32 v25, 0xffff0000, v27
	v_and_b32_e32 v24, 0xffff0000, v26
	v_mov_b32_e32 v37, v12
	v_mov_b32_e32 v12, v11
	v_lshlrev_b32_e32 v19, 16, v27
	v_lshlrev_b32_e32 v18, 16, v26
	v_mov_b32_e32 v26, v2
	v_mov_b32_e32 v27, v4
	v_mov_b32_e32 v36, v10
	v_mov_b32_e32 v4, v3
	v_pk_mul_f32 v[2:3], v[12:13], v[20:21]
	v_pk_mul_f32 v[12:13], v[12:13], v[24:25]
	v_pk_fma_f32 v[10:11], v[4:5], v[24:25], v[2:3]
	v_pk_mul_f32 v[2:3], v[36:37], v[18:19]
	v_pk_fma_f32 v[4:5], v[4:5], v[20:21], v[12:13] neg_lo:[0,0,1] neg_hi:[0,0,1]
	v_pk_fma_f32 v[44:45], v[40:41], v[38:39], v[44:45]
	v_pk_mul_f32 v[38:39], v[36:37], v[16:17]
	v_pk_fma_f32 v[2:3], v[26:27], v[16:17], v[2:3] neg_lo:[0,0,1] neg_hi:[0,0,1]
	v_bfe_u32 v12, v5, 16, 1
	v_bfe_u32 v13, v4, 16, 1
	v_bfe_u32 v16, v9, 16, 1
	v_bfe_u32 v17, v8, 16, 1
	v_add3_u32 v8, v8, v17, s0
	v_add3_u32 v9, v9, v16, s0
	v_add3_u32 v4, v4, v13, s0
	v_add3_u32 v5, v5, v12, s0
	v_bfe_u32 v12, v14, 16, 1
	v_bfe_u32 v13, v15, 16, 1
	v_bfe_u32 v16, v2, 16, 1
	v_bfe_u32 v17, v3, 16, 1
	v_add3_u32 v3, v3, v17, s0
	v_add3_u32 v2, v2, v16, s0
	v_add3_u32 v13, v15, v13, s0
	v_add3_u32 v12, v14, v12, s0
	v_lshrrev_b32_e32 v12, 16, v12
	v_lshrrev_b32_e32 v13, 16, v13
	v_lshrrev_b32_e32 v2, 16, v2
	v_lshrrev_b32_e32 v3, 16, v3
	v_pk_fma_f32 v[38:39], v[26:27], v[18:19], v[38:39]
	v_and_or_b32 v5, v5, s34, v3
	v_and_or_b32 v4, v4, s34, v2
	v_and_or_b32 v3, v9, s34, v13
	v_and_or_b32 v2, v8, s34, v12
	v_bfe_u32 v8, v11, 16, 1
	v_bfe_u32 v9, v10, 16, 1
	v_bfe_u32 v12, v7, 16, 1
	v_bfe_u32 v13, v6, 16, 1
	v_add3_u32 v6, v6, v13, s0
	v_add3_u32 v7, v7, v12, s0
	v_add3_u32 v10, v10, v9, s0
	v_add3_u32 v8, v11, v8, s0
	v_bfe_u32 v9, v44, 16, 1
	v_bfe_u32 v11, v45, 16, 1
	v_bfe_u32 v12, v38, 16, 1
	v_bfe_u32 v13, v39, 16, 1
	v_add3_u32 v13, v39, v13, s0
	v_add3_u32 v12, v38, v12, s0
	v_add3_u32 v11, v45, v11, s0
	v_add3_u32 v9, v44, v9, s0
	v_lshrrev_b32_e32 v14, 16, v9
	v_lshrrev_b32_e32 v11, 16, v11
	v_lshrrev_b32_e32 v12, 16, v12
	v_lshrrev_b32_e32 v9, 16, v13
	v_and_or_b32 v9, v8, s34, v9
	v_and_or_b32 v8, v10, s34, v12
	v_and_or_b32 v7, v7, s34, v11
	v_and_or_b32 v6, v6, s34, v14
	ds_write_b128 v199, v[2:5]
	ds_write_b128 v199, v[6:9] offset:2048
	global_load_dwordx4 v[2:5], v[32:33], off offset:80
	global_load_dwordx4 v[10:13], v[32:33], off offset:64
	global_load_dwordx4 v[6:9], v[34:35], off offset:80
	global_load_dwordx4 v[14:17], v[34:35], off offset:64
	global_load_dwordx4 v[18:21], v[22:23], off offset:288
	s_waitcnt vmcnt(3)
	v_mov_b32_e32 v34, v10
	global_load_dwordx4 v[22:25], v[22:23], off offset:352
	s_waitcnt vmcnt(2)
; __device__ __forceinline__ float bf2f(unsigned short b) { return __uint_as_float(((unsigned)b) << 16); }
; __device__ __forceinline__ unsigned pk2(float lo, float hi) { return f2bf(lo) | (f2bf(hi) << 16); }
; __device__ __forceinline__ int v_st(int k, int c) { const int kk = (k & ~0xC) | ((k & 4) << 1) | ((k & 8) >> 1); return ((kk >> 3) * 4 + (c >> 5)) * 512 + ((kk & 7) * 32 + (c & 31)) * 2; }
;     ...
;     const int qrow = q0 + wid * QBLK + r32;
; #pragma unroll
;     for (int pr = 0; pr < 2; ++pr) {
;       const bf16x8 xa = *reinterpret_cast<const bf16x8*>(Qw + (8 + pr) * 16), xb = *reinterpret_cast<const bf16x8*>(Qw + (10 + pr) * 16);
;       const float* cp = cosp + (size_t)qrow * 32 + pr * 16 + hi * 8; const float* sp = sinp + (size_t)qrow * 32 + pr * 16 + hi * 8;
;       const f32x4 c0 = *(const f32x4*)cp, c1 = *(const f32x4*)(cp + 4), s0 = *(const f32x4*)sp, s1 = *(const f32x4*)(sp + 4);
;       float ya[8], yb[8];
; #pragma unroll
;       for (int t = 0; t < 8; ++t) { const float x1 = bf2f((unsigned short)xa[t]), x2 = bf2f((unsigned short)xb[t]); const float c = t < 4 ? c0[t & 3] : c1[t & 3], sn = t < 4 ? s0[t & 3] : s1[t & 3];
;         ya[t] = x1 * c - x2 * sn; yb[t] = x2 * c + x1 * sn; }
;       u32x4 wa = {pk2(ya[0], ya[1]), pk2(ya[2], ya[3]), pk2(ya[4], ya[5]), pk2(ya[6], ya[7])}, wb = {pk2(yb[0], yb[1]), pk2(yb[2], yb[3]), pk2(yb[4], yb[5]), pk2(yb[6], yb[7])};
;       *reinterpret_cast<u32x4*>(qls + (8 + pr - (NDQ - NQL)) * 1024) = wa; *reinterpret_cast<u32x4*>(qls + (10 + pr - (NDQ - NQL)) * 1024) = wb; }
;     ...
;   const int sr = tid >> 4, sc = (tid & 15) * 8, vst0 = v_st(sr, sc), vst1 = v_st(32 + sr, sc);
;   const int sr8 = tid >> 3, sc8 = (tid & 7) * 8;
;   const int vb0 = (int)(uintptr_t)V_lds + v_rd_base(lane);
;   const int qlane = q0 + wid * QBLK + r32;
;   struct { bf16x8 vs0, vs1, ks0, ks1, ks2; } sr_[SDEPTH];
;   constexpr int SWM = (NDQ == 8) ? 15 : 7;
;     ...
;   f32x16 pA0, pA1, pB0, pB1; float alA, alB; bf16x8 pa0, pa1, pa2, pa3; const int NT = nkeys / KVBLK;
;   const int kb0 = (int)(uintptr_t)K_lds + r32 * ROWB + (((r32 & SWM) << 4) ^ (hi << 4));
;   const int qa0 = (int)(uintptr_t)qls;
;     ...
;   constexpr int SE = 0, SO = SDEPTH - 1;
;   SLOAD(SE, kbeg); asm volatile("s_waitcnt vmcnt(0)" ::: "memory"); SWRITE(0, SE); __syncthreads();
	v_mov_b32_e32 v36, v14
	s_waitcnt vmcnt(1)
	v_lshlrev_b32_e32 v27, 16, v19
	v_lshlrev_b32_e32 v26, 16, v18
	v_and_b32_e32 v19, 0xffff0000, v19
	v_and_b32_e32 v18, 0xffff0000, v18
	v_mov_b32_e32 v37, v16
	v_mov_b32_e32 v16, v15
	v_mov_b32_e32 v35, v12
	v_mov_b32_e32 v12, v11
	v_pk_mul_f32 v[10:11], v[16:17], v[18:19]
	v_pk_mul_f32 v[38:39], v[36:37], v[26:27]
	s_waitcnt vmcnt(0)
	v_lshlrev_b32_e32 v33, 16, v23
	v_lshlrev_b32_e32 v32, 16, v22
	v_and_b32_e32 v23, 0xffff0000, v23
	v_and_b32_e32 v22, 0xffff0000, v22
	v_pk_mul_f32 v[14:15], v[36:37], v[32:33]
	v_pk_mul_f32 v[16:17], v[16:17], v[22:23]
	v_pk_fma_f32 v[10:11], v[12:13], v[22:23], v[10:11]
	v_pk_fma_f32 v[14:15], v[34:35], v[26:27], v[14:15] neg_lo:[0,0,1] neg_hi:[0,0,1]
	v_pk_fma_f32 v[12:13], v[12:13], v[18:19], v[16:17] neg_lo:[0,0,1] neg_hi:[0,0,1]
	v_lshlrev_b32_e32 v17, 16, v21
	v_lshlrev_b32_e32 v16, 16, v20
	v_and_b32_e32 v21, 0xffff0000, v21
	v_and_b32_e32 v20, 0xffff0000, v20
	v_and_b32_e32 v23, 0xffff0000, v25
	v_and_b32_e32 v22, 0xffff0000, v24
	v_mov_b32_e32 v27, v8
	v_mov_b32_e32 v8, v7
	v_lshlrev_b32_e32 v19, 16, v25
	v_lshlrev_b32_e32 v18, 16, v24
	v_mov_b32_e32 v24, v2
	v_mov_b32_e32 v25, v4
	v_mov_b32_e32 v26, v6
	v_mov_b32_e32 v4, v3
	v_pk_mul_f32 v[2:3], v[8:9], v[20:21]
	v_pk_mul_f32 v[8:9], v[8:9], v[22:23]
	v_pk_fma_f32 v[6:7], v[4:5], v[22:23], v[2:3]
	v_pk_mul_f32 v[2:3], v[26:27], v[18:19]
	v_pk_fma_f32 v[4:5], v[4:5], v[20:21], v[8:9] neg_lo:[0,0,1] neg_hi:[0,0,1]
	v_pk_fma_f32 v[38:39], v[34:35], v[32:33], v[38:39]
	v_pk_mul_f32 v[32:33], v[26:27], v[16:17]
	v_pk_fma_f32 v[2:3], v[24:25], v[16:17], v[2:3] neg_lo:[0,0,1] neg_hi:[0,0,1]
	v_bfe_u32 v8, v5, 16, 1
	v_bfe_u32 v9, v4, 16, 1
	v_bfe_u32 v16, v13, 16, 1
	v_bfe_u32 v17, v12, 16, 1
	v_add3_u32 v12, v12, v17, s0
	v_add3_u32 v13, v13, v16, s0
	v_add3_u32 v4, v4, v9, s0
	v_add3_u32 v5, v5, v8, s0
	v_bfe_u32 v8, v14, 16, 1
	v_bfe_u32 v9, v15, 16, 1
	v_bfe_u32 v16, v2, 16, 1
	v_bfe_u32 v17, v3, 16, 1
	v_add3_u32 v3, v3, v17, s0
	v_add3_u32 v2, v2, v16, s0
	v_add3_u32 v9, v15, v9, s0
	v_add3_u32 v8, v14, v8, s0
	v_lshrrev_b32_e32 v8, 16, v8
	v_lshrrev_b32_e32 v9, 16, v9
	v_lshrrev_b32_e32 v2, 16, v2
	v_lshrrev_b32_e32 v3, 16, v3
	v_pk_fma_f32 v[32:33], v[24:25], v[18:19], v[32:33]
	v_and_or_b32 v5, v5, s34, v3
	v_and_or_b32 v4, v4, s34, v2
	v_and_or_b32 v3, v13, s34, v9
	v_and_or_b32 v2, v12, s34, v8
	v_bfe_u32 v8, v7, 16, 1
	v_bfe_u32 v9, v6, 16, 1
	v_bfe_u32 v12, v11, 16, 1
	v_bfe_u32 v13, v10, 16, 1
	v_add3_u32 v10, v10, v13, s0
	v_add3_u32 v11, v11, v12, s0
	v_add3_u32 v6, v6, v9, s0
	v_add3_u32 v7, v7, v8, s0
	v_bfe_u32 v8, v38, 16, 1
	v_bfe_u32 v9, v39, 16, 1
	v_bfe_u32 v12, v32, 16, 1
	v_bfe_u32 v13, v33, 16, 1
	v_add3_u32 v13, v33, v13, s0
	v_add3_u32 v12, v32, v12, s0
	v_add3_u32 v9, v39, v9, s0
	v_add3_u32 v8, v38, v8, s0
	v_lshrrev_b32_e32 v14, 16, v8
	v_lshrrev_b32_e32 v15, 16, v9
	v_lshrrev_b32_e32 v8, 16, v12
	v_lshrrev_b32_e32 v9, 16, v13
	v_ashrrev_i32_e32 v22, 4, v30
	v_and_or_b32 v9, v7, s34, v9
	v_and_or_b32 v8, v6, s34, v8
	v_and_or_b32 v7, v11, s34, v15
	v_and_or_b32 v6, v10, s34, v14
	ds_write_b128 v199, v[2:5] offset:1024
	ds_write_b128 v199, v[6:9] offset:3072
	v_and_b32_e32 v4, 0xfffff0, v22
	v_lshlrev_b32_e32 v5, 1, v22
	v_lshlrev_b32_e32 v2, 3, v56
	v_and_or_b32 v4, v22, 8, v4
	v_and_b32_e32 v3, 0x78, v2
	v_lshrrev_b32_e32 v5, 1, v22
	v_lshrrev_b32_e32 v4, 1, v4
	v_bfe_u32 v2, v2, 5, 2
	v_and_b32_e32 v6, 3, v22
	v_or_b32_e32 v4, v4, v2
	v_and_or_b32 v5, v22, 4, v6
	v_lshlrev_b32_e32 v24, 1, v3
	v_lshlrev_b32_e32 v4, 9, v4
	v_lshlrev_b32_e32 v5, 6, v5
	v_and_b32_e32 v3, 48, v24
	v_add_u32_e32 v6, 32, v22
	v_or3_b32 v31, v4, v5, v3
	v_and_b32_e32 v4, 0xfffff0, v6
	v_lshlrev_b32_e32 v7, 1, v6
	v_and_or_b32 v4, v6, 8, v4
	v_lshrrev_b32_e32 v4, 1, v4
	v_or_b32_e32 v2, v4, v2
	v_lshlrev_b32_e32 v2, 9, v2
	v_or3_b32 v32, v2, v5, v3
	v_lshlrev_b32_e32 v2, 3, v57
	v_and_b32_e32 v3, 0xc0, v28
	v_lshlrev_b32_e32 v4, 1, v56
	v_and_or_b32 v3, v2, 24, v3
	v_and_b32_e32 v4, 32, v4
	v_and_b32_e32 v2, 0x100, v2
	v_or3_b32 v59, v3, v4, v2
	v_bitop3_b32 v3, v198, v56, 7 bitop3:0x78
	v_ashrrev_i32_e32 v23, 31, v22
	v_mul_u32_u24_e32 v2, 0x180, v0
	v_lshlrev_b32_e32 v3, 4, v3
	v_lshlrev_b64 v[50:51], 11, v[22:23]
	v_add3_u32 v209, v2, s4, v3
	v_lshl_add_u64 v[2:3], s[60:61], 0, v[50:51]
	v_mov_b32_e32 v25, v1
	v_ashrrev_i32_e32 v26, 3, v30
	v_lshl_add_u64 v[52:53], v[2:3], 0, v[24:25]
	global_load_dwordx4 v[2:5], v[52:53], off offset:256
	v_ashrrev_i32_e32 v7, 31, v6
	v_ashrrev_i32_e32 v27, 31, v26
	v_lshlrev_b64 v[6:7], 11, v[6:7]
	v_lshlrev_b64 v[186:187], 7, v[26:27]
	v_lshlrev_b32_e32 v20, 4, v56
	v_lshl_add_u64 v[6:7], s[60:61], 0, v[6:7]
	v_lshl_add_u64 v[18:19], s[8:9], 0, v[186:187]
	v_and_b32_e32 v28, 0x70, v20
	v_lshl_add_u64 v[10:11], v[6:7], 0, v[24:25]
	v_lshl_add_u64 v[54:55], v[18:19], 0, v[28:29]
	global_load_dwordx4 v[6:9], v[10:11], off offset:256
	global_load_dwordx4 v[14:17], v[52:53], off
	s_nop 0
	global_load_dwordx4 v[10:13], v[10:11], off
	v_add_u32_e32 v210, 0, v31
	global_load_dwordx4 v[18:21], v[54:55], off
	s_movk_i32 s4, 0x180
	s_waitcnt vmcnt(0)
	v_add_u32_e32 v211, 0, v32
	v_xor_b32_e32 v215, 32, v209
	v_add_u32_e32 v201, s6, v59
	s_waitcnt vmcnt(4)
	ds_write_b128 v210, v[2:5]
	v_mul_lo_u32 v2, v22, s4
	v_bitop3_b32 v3, v24, v30, s5 bitop3:0x78
	v_lshlrev_b32_e32 v4, 4, v26
	v_add3_u32 v212, v3, v2, 0
	v_mul_lo_u32 v2, v26, s4
	v_or_b32_e32 v3, 0x100, v28
	v_and_b32_e32 v4, 0x70, v4
	v_xad_u32 v2, v3, v4, v2
	v_add_u32_e32 v214, 0, v2
	s_waitcnt vmcnt(3)
	ds_write_b128 v211, v[6:9]
	s_waitcnt vmcnt(2)
	ds_write_b128 v212, v[14:17] offset:32768
	s_waitcnt vmcnt(1)
	ds_write_b128 v212, v[10:13] offset:45056
	s_waitcnt vmcnt(0)
	ds_write_b128 v214, v[18:21] offset:32768
	s_waitcnt lgkmcnt(0)
	s_barrier
; __device__ __forceinline__ void qkt12_roll(f32x16& p0, f32x16& p1, const f32x16& negm, int kb, int qa, const bf16x8* qr) {
;   const int a0 = kb ^ (0 << 5); const bf16x8 x0 = lds_rd128<0>(a0), y0 = lds_rd128<12288>(a0);
;   const int a1 = kb ^ (1 << 5); const bf16x8 x1 = lds_rd128<0>(a1), y1 = lds_rd128<12288>(a1);
;   asm volatile("s_waitcnt lgkmcnt(2)" ::: "memory"); SBAR();
;   p0 = __builtin_amdgcn_mfma_f32_32x32x16_bf16(x0, qr[0], negm, 0, 0, 0); p1 = __builtin_amdgcn_mfma_f32_32x32x16_bf16(y0, qr[0], negm, 0, 0, 0);
;   const int a2 = kb ^ (2 << 5); const bf16x8 x2 = lds_rd128<0>(a2), y2 = lds_rd128<12288>(a2);
;   asm volatile("s_waitcnt lgkmcnt(2)" ::: "memory"); SBAR();
;   p0 = __builtin_amdgcn_mfma_f32_32x32x16_bf16(x1, qr[1], p0, 0, 0, 0); p1 = __builtin_amdgcn_mfma_f32_32x32x16_bf16(y1, qr[1], p1, 0, 0, 0);
;   const int a3 = kb ^ (3 << 5); const bf16x8 x3 = lds_rd128<0>(a3), y3 = lds_rd128<12288>(a3);
;   asm volatile("s_waitcnt lgkmcnt(2)" ::: "memory"); SBAR();
;   p0 = __builtin_amdgcn_mfma_f32_32x32x16_bf16(x2, qr[2], p0, 0, 0, 0); p1 = __builtin_amdgcn_mfma_f32_32x32x16_bf16(y2, qr[2], p1, 0, 0, 0);
;   const int a4 = kb ^ (0 << 5); const bf16x8 x4 = lds_rd128<128>(a4), y4 = lds_rd128<12416>(a4);
;   asm volatile("s_waitcnt lgkmcnt(2)" ::: "memory"); SBAR();
;   p0 = __builtin_amdgcn_mfma_f32_32x32x16_bf16(x3, qr[3], p0, 0, 0, 0); p1 = __builtin_amdgcn_mfma_f32_32x32x16_bf16(y3, qr[3], p1, 0, 0, 0);
;   const int a5 = kb ^ (1 << 5); const bf16x8 x5 = lds_rd128<128>(a5), y5 = lds_rd128<12416>(a5);
;   asm volatile("s_waitcnt lgkmcnt(2)" ::: "memory"); SBAR();
;   p0 = __builtin_amdgcn_mfma_f32_32x32x16_bf16(x4, qr[4], p0, 0, 0, 0); p1 = __builtin_amdgcn_mfma_f32_32x32x16_bf16(y4, qr[4], p1, 0, 0, 0);
;   const int a6 = kb ^ (2 << 5); const bf16x8 x6 = lds_rd128<128>(a6), y6 = lds_rd128<12416>(a6);
;   asm volatile("s_waitcnt lgkmcnt(2)" ::: "memory"); SBAR();
;   p0 = __builtin_amdgcn_mfma_f32_32x32x16_bf16(x5, qr[5], p0, 0, 0, 0); p1 = __builtin_amdgcn_mfma_f32_32x32x16_bf16(y5, qr[5], p1, 0, 0, 0);
;   const int a7 = kb ^ (3 << 5); const bf16x8 x7 = lds_rd128<128>(a7), y7 = lds_rd128<12416>(a7);
;   asm volatile("s_waitcnt lgkmcnt(2)" ::: "memory"); SBAR();
;   p0 = __builtin_amdgcn_mfma_f32_32x32x16_bf16(x6, qr[6], p0, 0, 0, 0); p1 = __builtin_amdgcn_mfma_f32_32x32x16_bf16(y6, qr[6], p1, 0, 0, 0);
	ds_read_b128 v[2:5], v209 offset:0
	ds_read_b128 v[18:21], v209 offset:0x3000
	ds_read_b128 v[60:63], v215 offset:0
	ds_read_b128 v[64:67], v215 offset:0x3000
	s_waitcnt lgkmcnt(2)
	v_add_u32_e32 v213, 0x3000, v212
	v_mfma_f32_32x32x16_bf16 v[34:49], v[2:5], v[158:161], 0
	v_xor_b32_e32 v216, 64, v209
	ds_read_b128 v[68:71], v216 offset:0
	ds_read_b128 v[72:75], v216 offset:0x3000
	s_mov_b32 s13, s12
	s_waitcnt lgkmcnt(2)
	s_mov_b32 s14, s12
	s_mov_b32 s15, s12
	v_mfma_f32_32x32x16_bf16 v[18:33], v[18:21], v[158:161], 0
	s_mov_b32 s16, s12
	s_mov_b32 s17, s12
	s_mov_b32 s18, s12
	s_mov_b32 s19, s12
	s_mov_b32 s20, s12
	s_mov_b32 s21, s12
	s_mov_b32 s22, s12
	s_mov_b32 s23, s12
	s_mov_b32 s24, s12
	s_mov_b32 s25, s12
	s_mov_b32 s26, s12
	s_mov_b32 s27, s12
	v_mov_b64_e32 v[2:3], s[12:13]
	v_mov_b64_e32 v[4:5], s[14:15]
	v_mov_b64_e32 v[6:7], s[16:17]
	v_mov_b64_e32 v[8:9], s[18:19]
	v_mov_b64_e32 v[10:11], s[20:21]
	v_mov_b64_e32 v[12:13], s[22:23]
	v_mov_b64_e32 v[14:15], s[24:25]
	v_mov_b64_e32 v[16:17], s[26:27]
	v_mfma_f32_32x32x16_bf16 v[34:49], v[60:63], v[154:157], v[34:49]
	v_xor_b32_e32 v217, 0x60, v209
	ds_read_b128 v[60:63], v217 offset:0
	v_mfma_f32_32x32x16_bf16 v[18:33], v[64:67], v[154:157], v[18:33]
	ds_read_b128 v[64:67], v217 offset:0x3000
	s_waitcnt lgkmcnt(2)
	v_mfma_f32_32x32x16_bf16 v[34:49], v[68:71], v[150:153], v[34:49]
	ds_read_b128 v[68:71], v209 offset:0x80
	v_mfma_f32_32x32x16_bf16 v[18:33], v[72:75], v[150:153], v[18:33]
	ds_read_b128 v[72:75], v209 offset:0x3080
	s_waitcnt lgkmcnt(2)
	v_mfma_f32_32x32x16_bf16 v[34:49], v[60:63], v[146:149], v[34:49]
	ds_read_b128 v[60:63], v215 offset:0x80
	v_mfma_f32_32x32x16_bf16 v[18:33], v[64:67], v[146:149], v[18:33]
	ds_read_b128 v[64:67], v215 offset:0x3080
	s_waitcnt lgkmcnt(2)
	v_mfma_f32_32x32x16_bf16 v[34:49], v[68:71], v[142:145], v[34:49]
	ds_read_b128 v[68:71], v216 offset:0x80
	v_mfma_f32_32x32x16_bf16 v[18:33], v[72:75], v[142:145], v[18:33]
	ds_read_b128 v[72:75], v216 offset:0x3080
	s_waitcnt lgkmcnt(2)
	v_mfma_f32_32x32x16_bf16 v[34:49], v[60:63], v[138:141], v[34:49]
	ds_read_b128 v[60:63], v217 offset:0x80
	v_mfma_f32_32x32x16_bf16 v[18:33], v[64:67], v[138:141], v[18:33]
	ds_read_b128 v[64:67], v217 offset:0x3080
	s_waitcnt lgkmcnt(2)
	v_mfma_f32_32x32x16_bf16 v[34:49], v[68:71], v[134:137], v[34:49]
	ds_read_b128 v[68:71], v209 offset:0x100
	v_mfma_f32_32x32x16_bf16 v[18:33], v[72:75], v[134:137], v[18:33]
	ds_read_b128 v[72:75], v209 offset:0x3100
	ds_read_b128 v[76:79], v199 offset:0
	s_waitcnt lgkmcnt(3)
	v_mfma_f32_32x32x16_bf16 v[34:49], v[60:63], v[130:133], v[34:49]
	ds_read_b128 v[60:63], v215 offset:0x100
	v_mfma_f32_32x32x16_bf16 v[18:33], v[64:67], v[130:133], v[18:33]
	ds_read_b128 v[64:67], v215 offset:0x3100
	ds_read_b128 v[80:83], v199 offset:0x400
	s_waitcnt lgkmcnt(3)
	v_mfma_f32_32x32x16_bf16 v[34:49], v[68:71], v[76:79], v[34:49]
	ds_read_b128 v[68:71], v216 offset:0x100
	v_mfma_f32_32x32x16_bf16 v[18:33], v[72:75], v[76:79], v[18:33]
	ds_read_b128 v[72:75], v216 offset:0x3100
	ds_read_b128 v[76:79], v199 offset:0x800
	s_waitcnt lgkmcnt(3)
	v_mfma_f32_32x32x16_bf16 v[34:49], v[60:63], v[80:83], v[34:49]
	ds_read_b128 v[60:63], v217 offset:0x100
	v_mfma_f32_32x32x16_bf16 v[18:33], v[64:67], v[80:83], v[18:33]
	ds_read_b128 v[64:67], v217 offset:0x3100
	ds_read_b128 v[80:83], v199 offset:0xc00
	s_waitcnt lgkmcnt(3)
	v_mfma_f32_32x32x16_bf16 v[34:49], v[68:71], v[76:79], v[34:49]
	s_waitcnt lgkmcnt(0)
; #define SWAIT() do { if constexpr (SDEPTH == 2) { if constexpr (NDQ == 4) asm volatile("s_waitcnt vmcnt(3)" ::: "memory"); else if constexpr (NDQ == 8) asm volatile("s_waitcnt vmcnt(4)" ::: "memory"); else asm volatile("s_waitcnt vmcnt(5)" ::: "memory"); } \
;     else asm volatile("s_waitcnt vmcnt(0)" ::: "memory"); } while (0)
; template <bool FIRST>
; __device__ __forceinline__ void partialSM(f32x16& p0, f32x16& p1, float& mC, float& alpha) {
;   float mx_[4] = {p0[0], p0[1], p0[2], p0[3]};
; #pragma unroll
;   for (int r = 4; r < 16; ++r) mx_[r & 3] = fmaxf(mx_[r & 3], p0[r]);
; #pragma unroll
;   for (int r = 0; r < 16; ++r) mx_[r & 3] = fmaxf(mx_[r & 3], p1[r]);
;   float pmax = fmaxf(fmaxf(mx_[0], mx_[1]), fmaxf(mx_[2], mx_[3]));
;   { auto rr = __builtin_amdgcn_permlane32_swap(__float_as_uint(pmax), __float_as_uint(pmax), false, false);
;     pmax = fmaxf(__uint_as_float(rr[0]), __uint_as_float(rr[1])); }
;   if (!FIRST && __builtin_expect(__all(pmax <= THR2), 1)) { alpha = 1.f; }
;   else { const float delta = FIRST ? fmaxf(pmax, -200.f) : fmaxf(pmax, 0.f); alpha = FIRST ? 1.f : __builtin_amdgcn_exp2f(-delta); mC += delta;
; #pragma unroll
;     for (int r = 0; r < 16; ++r) p0[r] -= delta;
; #pragma unroll
;     for (int r = 0; r < 16; ++r) p1[r] -= delta; }
; #pragma unroll
;   for (int r = 0; r < 16; ++r) p0[r] = __builtin_amdgcn_exp2f(p0[r]);
; }
;     ...
;   f32x16 pA0, pA1, pB0, pB1; float alA, alB; bf16x8 pa0, pa1, pa2, pa3; const int NT = nkeys / KVBLK;
;   const int kb0 = (int)(uintptr_t)K_lds + r32 * ROWB + (((r32 & SWM) << 4) ^ (hi << 4));
;   const int qa0 = (int)(uintptr_t)qls;
;     ...
;   constexpr int SE = 0, SO = SDEPTH - 1;
;   SLOAD(SE, kbeg); asm volatile("s_waitcnt vmcnt(0)" ::: "memory"); SWRITE(0, SE); __syncthreads();
;   constexpr bool SLICED = (NDQ == 8 && NQL == 0 && BIAS == 1);
;   NEGM_UPD(kbeg); QKT(pA0, pA1, 0); BIASADD(pA0, pA1, kbeg); partialSM<true>(pA0, pA1, mC, alA);
;   if constexpr (SLICED) {
; #pragma unroll
;     for (int r = 0; r < 16; ++r) pA1[r] = __builtin_amdgcn_exp2f(pA1[r]); }
;   SLOAD(SO, kbeg + KVBLK); if constexpr (SDEPTH == 2) { if (2 < NT) SLOAD(SE, kbeg + 2 * KVBLK); }
;   SWAIT(); SWRITE(1, SO); __syncthreads();
	v_mfma_f32_32x32x16_bf16 v[18:33], v[72:75], v[76:79], v[18:33]
	v_mfma_f32_32x32x16_bf16 v[34:49], v[60:63], v[80:83], v[34:49]
	v_mfma_f32_32x32x16_bf16 v[18:33], v[64:67], v[80:83], v[18:33]
	s_mov_b64 s[4:5], 0x20000
	v_lshl_add_u64 v[60:61], v[52:53], 0, s[4:5]
	s_mov_b64 s[4:5], 0x30000
	v_lshl_add_u64 v[64:65], v[52:53], 0, s[4:5]
	s_mov_b32 s4, 0x20000
	global_load_dwordx4 v[60:63], v[60:61], off offset:256
	s_nop 0
	global_load_dwordx4 v[82:85], v[64:65], off offset:256
	v_add_co_u32_e32 v64, vcc, s4, v52
	s_mov_b32 s4, 0x30000
	s_nop 0
	v_addc_co_u32_e32 v65, vcc, 0, v53, vcc
	v_add_co_u32_e32 v52, vcc, s4, v52
	s_movk_i32 s4, 0x2000
	s_nop 0
	v_addc_co_u32_e32 v53, vcc, 0, v53, vcc
	global_load_dwordx4 v[86:89], v[64:65], off
	global_load_dwordx4 v[90:93], v[52:53], off
	v_add_co_u32_e32 v52, vcc, s4, v54
	v_max_f32_e32 v66, v38, v38
	s_nop 0
	v_addc_co_u32_e32 v53, vcc, 0, v55, vcc
	global_load_dwordx4 v[52:55], v[52:53], off
	v_max_f32_e32 v67, v34, v34
	v_max_f32_e32 v64, v67, v66
	v_max_f32_e32 v65, v39, v39
	v_max_f32_e32 v66, v35, v35
	v_max_f32_e32 v65, v66, v65
	v_max_f32_e32 v66, v41, v41
	v_max_f32_e32 v67, v37, v37
	v_max_f32_e32 v66, v67, v66
	v_max3_f32 v67, v36, v40, v44
	v_max3_f32 v66, v66, v45, v49
	v_max3_f32 v64, v64, v42, v46
	v_max3_f32 v65, v65, v43, v47
	v_max3_f32 v67, v67, v48, v20
	v_max3_f32 v66, v66, v21, v25
	v_max3_f32 v64, v64, v18, v22
	v_max3_f32 v65, v65, v19, v23
	v_max3_f32 v67, v67, v24, v28
	v_max3_f32 v66, v66, v29, v33
	v_max3_f32 v64, v64, v26, v30
	v_max3_f32 v65, v65, v27, v31
	v_max3_f32 v66, v67, v32, v66
	v_max3_f32 v64, v64, v65, v66
	v_mov_b32_e32 v65, v64
	s_nop 1
	v_permlane32_swap_b32_e32 v64, v65
	s_mov_b32 s4, 0xc3480000
	v_max3_f32 v64, v64, v65, s4
	v_sub_f32_e32 v34, v34, v64
	v_sub_f32_e32 v35, v35, v64
	v_sub_f32_e32 v36, v36, v64
	v_sub_f32_e32 v37, v37, v64
	v_sub_f32_e32 v38, v38, v64
	v_sub_f32_e32 v39, v39, v64
	v_sub_f32_e32 v40, v40, v64
	v_sub_f32_e32 v41, v41, v64
	v_sub_f32_e32 v42, v42, v64
	v_sub_f32_e32 v43, v43, v64
	v_sub_f32_e32 v44, v44, v64
	v_sub_f32_e32 v45, v45, v64
	v_sub_f32_e32 v46, v46, v64
	v_sub_f32_e32 v47, v47, v64
	v_sub_f32_e32 v48, v48, v64
	v_sub_f32_e32 v49, v49, v64
	v_sub_f32_e32 v66, v18, v64
	v_exp_f32_e32 v176, v34
	v_exp_f32_e32 v178, v35
	v_exp_f32_e32 v167, v36
	v_exp_f32_e32 v177, v37
	v_exp_f32_e32 v168, v38
	v_exp_f32_e32 v175, v39
	v_exp_f32_e32 v169, v40
	v_exp_f32_e32 v174, v41
	v_exp_f32_e32 v170, v42
	v_exp_f32_e32 v173, v43
	v_exp_f32_e32 v165, v44
	v_exp_f32_e32 v171, v45
	v_exp_f32_e32 v163, v46
	v_exp_f32_e32 v172, v47
	v_exp_f32_e32 v162, v48
	v_exp_f32_e32 v164, v49
	v_and_b32_e32 v18, 15, v56
	v_sub_f32_e32 v67, v19, v64
	s_waitcnt vmcnt(0)
	s_addk_i32 s6, 0x4000
	v_or_b32_e32 v50, s59, v50
	v_lshlrev_b32_e32 v18, 4, v18
	v_mov_b32_e32 v19, v1
	v_add_f32_e32 v225, 0, v64
	v_sub_f32_e32 v81, v33, v64
	v_sub_f32_e32 v80, v32, v64
	v_sub_f32_e32 v79, v31, v64
	v_sub_f32_e32 v78, v30, v64
	v_sub_f32_e32 v77, v29, v64
	v_sub_f32_e32 v76, v28, v64
	v_sub_f32_e32 v75, v27, v64
	v_sub_f32_e32 v74, v26, v64
	v_sub_f32_e32 v73, v25, v64
	v_sub_f32_e32 v72, v24, v64
	v_sub_f32_e32 v71, v23, v64
	v_sub_f32_e32 v70, v22, v64
	v_sub_f32_e32 v69, v21, v64
	v_sub_f32_e32 v68, v20, v64
	s_waitcnt vmcnt(4)
	ds_write_b128 v210, v[60:63] offset:16384
	s_waitcnt vmcnt(3)
	ds_write_b128 v211, v[82:85] offset:16384
	s_waitcnt vmcnt(2)
	ds_write_b128 v212, v[86:89] offset:57344
	s_waitcnt vmcnt(1)
	ds_write_b128 v213, v[90:93] offset:57344
	s_waitcnt vmcnt(0)
	ds_write_b128 v214, v[52:55] offset:57344
	v_add_u32_e32 v221, 0x6000, v209
	v_cmp_gt_u32_e64 s[4:5], 32, v57
	v_add_u32_e32 v208, s6, v59
	v_lshl_add_u64 v[188:189], v[50:51], 0, v[18:19]
	v_lshl_or_b32 v186, v58, 4, v186
	v_mov_b32_e32 v228, 0
	v_mov_b64_e32 v[64:65], v[16:17]
	v_mov_b64_e32 v[48:49], v[16:17]
	v_mov_b64_e32 v[32:33], v[16:17]
	v_xor_b32_e32 v220, 32, v221
	v_xor_b32_e32 v219, 64, v221
	v_xor_b32_e32 v218, 0x60, v221
	v_lshl_add_u32 v200, v0, 2, v183
	v_add_u32_e32 v185, v183, v184
	v_mov_b32_e32 v222, 1.0
	v_mov_b64_e32 v[62:63], v[14:15]
	v_mov_b64_e32 v[60:61], v[12:13]
	v_mov_b64_e32 v[58:59], v[10:11]
	v_mov_b64_e32 v[56:57], v[8:9]
	v_mov_b64_e32 v[54:55], v[6:7]
	v_mov_b64_e32 v[52:53], v[4:5]
	v_mov_b64_e32 v[50:51], v[2:3]
	v_mov_b64_e32 v[46:47], v[14:15]
	v_mov_b64_e32 v[44:45], v[12:13]
	v_mov_b64_e32 v[42:43], v[10:11]
	v_mov_b64_e32 v[40:41], v[8:9]
	v_mov_b64_e32 v[38:39], v[6:7]
	v_mov_b64_e32 v[36:37], v[4:5]
	v_mov_b64_e32 v[34:35], v[2:3]
	v_mov_b64_e32 v[30:31], v[14:15]
	v_mov_b64_e32 v[28:29], v[12:13]
	v_mov_b64_e32 v[26:27], v[10:11]
	v_mov_b64_e32 v[24:25], v[8:9]
	v_mov_b64_e32 v[22:23], v[6:7]
	v_mov_b64_e32 v[20:21], v[4:5]
	v_mov_b64_e32 v[18:19], v[2:3]
	v_mov_b32_e32 v207, 0
	v_mov_b32_e32 v98, 0
	v_mov_b32_e32 v99, v228
	v_mov_b32_e32 v100, v228
	v_mov_b32_e32 v101, v228
	v_mov_b32_e32 v102, v228
	v_mov_b32_e32 v103, v228
	v_mov_b32_e32 v104, v228
	v_mov_b32_e32 v105, v228
	v_mov_b32_e32 v106, v228
	v_mov_b32_e32 v107, v228
	v_mov_b32_e32 v108, v228
	v_mov_b32_e32 v109, v228
	v_mov_b32_e32 v110, v228
	v_mov_b32_e32 v111, v228
	v_mov_b32_e32 v112, v228
	v_mov_b32_e32 v113, v228
	ds_read_b128 v[192:195], v199 offset:0
	ds_read_b128 v[202:205], v199 offset:0x400
	s_waitcnt lgkmcnt(0)
	s_waitcnt lgkmcnt(0)
	s_barrier

; __device__ __forceinline__ void qkt12_roll(f32x16& p0, f32x16& p1, const f32x16& negm, int kb, int qa, const bf16x8* qr) {
;   const int a0 = kb ^ (0 << 5); const bf16x8 x0 = lds_rd128<0>(a0), y0 = lds_rd128<12288>(a0);
;   const int a1 = kb ^ (1 << 5); const bf16x8 x1 = lds_rd128<0>(a1), y1 = lds_rd128<12288>(a1);
;   asm volatile("s_waitcnt lgkmcnt(2)" ::: "memory"); SBAR();
;   p0 = __builtin_amdgcn_mfma_f32_32x32x16_bf16(x0, qr[0], negm, 0, 0, 0); p1 = __builtin_amdgcn_mfma_f32_32x32x16_bf16(y0, qr[0], negm, 0, 0, 0);
;   const int a2 = kb ^ (2 << 5); const bf16x8 x2 = lds_rd128<0>(a2), y2 = lds_rd128<12288>(a2);
;   asm volatile("s_waitcnt lgkmcnt(2)" ::: "memory"); SBAR();
;   p0 = __builtin_amdgcn_mfma_f32_32x32x16_bf16(x1, qr[1], p0, 0, 0, 0); p1 = __builtin_amdgcn_mfma_f32_32x32x16_bf16(y1, qr[1], p1, 0, 0, 0);
;   const int a3 = kb ^ (3 << 5); const bf16x8 x3 = lds_rd128<0>(a3), y3 = lds_rd128<12288>(a3);
;   asm volatile("s_waitcnt lgkmcnt(2)" ::: "memory"); SBAR();
;   p0 = __builtin_amdgcn_mfma_f32_32x32x16_bf16(x2, qr[2], p0, 0, 0, 0); p1 = __builtin_amdgcn_mfma_f32_32x32x16_bf16(y2, qr[2], p1, 0, 0, 0);
;   const int a4 = kb ^ (0 << 5); const bf16x8 x4 = lds_rd128<128>(a4), y4 = lds_rd128<12416>(a4);
;   asm volatile("s_waitcnt lgkmcnt(2)" ::: "memory"); SBAR();
;   p0 = __builtin_amdgcn_mfma_f32_32x32x16_bf16(x3, qr[3], p0, 0, 0, 0); p1 = __builtin_amdgcn_mfma_f32_32x32x16_bf16(y3, qr[3], p1, 0, 0, 0);
;   const int a5 = kb ^ (1 << 5); const bf16x8 x5 = lds_rd128<128>(a5), y5 = lds_rd128<12416>(a5);
;   asm volatile("s_waitcnt lgkmcnt(2)" ::: "memory"); SBAR();
;   p0 = __builtin_amdgcn_mfma_f32_32x32x16_bf16(x4, qr[4], p0, 0, 0, 0); p1 = __builtin_amdgcn_mfma_f32_32x32x16_bf16(y4, qr[4], p1, 0, 0, 0);
;   const int a6 = kb ^ (2 << 5); const bf16x8 x6 = lds_rd128<128>(a6), y6 = lds_rd128<12416>(a6);
;   asm volatile("s_waitcnt lgkmcnt(2)" ::: "memory"); SBAR();
;   p0 = __builtin_amdgcn_mfma_f32_32x32x16_bf16(x5, qr[5], p0, 0, 0, 0); p1 = __builtin_amdgcn_mfma_f32_32x32x16_bf16(y5, qr[5], p1, 0, 0, 0);
;   const int a7 = kb ^ (3 << 5); const bf16x8 x7 = lds_rd128<128>(a7), y7 = lds_rd128<12416>(a7);
;   asm volatile("s_waitcnt lgkmcnt(2)" ::: "memory"); SBAR();
;   p0 = __builtin_amdgcn_mfma_f32_32x32x16_bf16(x6, qr[6], p0, 0, 0, 0); p1 = __builtin_amdgcn_mfma_f32_32x32x16_bf16(y6, qr[6], p1, 0, 0, 0);
.Lmy_negm_skip_0:
	ds_read_b128 v[82:85], v221 offset:0
	ds_read_b128 v[230:233], v221 offset:0x3000
	ds_read_b128 v[234:237], v220 offset:0
	ds_read_b128 v[238:241], v220 offset:0x3000
	s_waitcnt lgkmcnt(2)
	s_nop 1
	v_mfma_f32_32x32x16_bf16 v[114:129], v[82:85], v[158:161], v[98:113]
	v_mfma_f32_32x32x16_bf16 v[82:97], v[230:233], v[158:161], v[98:113]
	ds_read_b128 v[230:233], v219 offset:0
	ds_read_b128 v[242:245], v219 offset:0x3000
	s_waitcnt lgkmcnt(2)
	v_mfma_f32_32x32x16_bf16 v[114:129], v[234:237], v[154:157], v[114:129]
	ds_read_b128 v[234:237], v218 offset:0
	v_mfma_f32_32x32x16_bf16 v[82:97], v[238:241], v[154:157], v[82:97]
	ds_read_b128 v[238:241], v218 offset:0x3000
	s_waitcnt lgkmcnt(2)
	v_mfma_f32_32x32x16_bf16 v[114:129], v[230:233], v[150:153], v[114:129]
	ds_read_b128 v[230:233], v221 offset:0x80
	v_mfma_f32_32x32x16_bf16 v[82:97], v[242:245], v[150:153], v[82:97]
	ds_read_b128 v[242:245], v221 offset:0x3080
	s_waitcnt lgkmcnt(2)
	v_mfma_f32_32x32x16_bf16 v[114:129], v[234:237], v[146:149], v[114:129]
	ds_read_b128 v[234:237], v220 offset:0x80
	v_mfma_f32_32x32x16_bf16 v[82:97], v[238:241], v[146:149], v[82:97]
	ds_read_b128 v[238:241], v220 offset:0x3080
	s_waitcnt lgkmcnt(2)
	v_mfma_f32_32x32x16_bf16 v[114:129], v[230:233], v[142:145], v[114:129]
	ds_read_b128 v[230:233], v219 offset:0x80
	v_mfma_f32_32x32x16_bf16 v[82:97], v[242:245], v[142:145], v[82:97]
	ds_read_b128 v[242:245], v219 offset:0x3080
	s_waitcnt lgkmcnt(2)
	v_mfma_f32_32x32x16_bf16 v[114:129], v[234:237], v[138:141], v[114:129]
	ds_read_b128 v[234:237], v218 offset:0x80
	v_mfma_f32_32x32x16_bf16 v[82:97], v[238:241], v[138:141], v[82:97]
	ds_read_b128 v[238:241], v218 offset:0x3080
	s_waitcnt lgkmcnt(2)
	v_mfma_f32_32x32x16_bf16 v[114:129], v[230:233], v[134:137], v[114:129]
	ds_read_b128 v[230:233], v221 offset:0x100
	v_mfma_f32_32x32x16_bf16 v[82:97], v[242:245], v[134:137], v[82:97]
	ds_read_b128 v[242:245], v221 offset:0x3100
	s_waitcnt lgkmcnt(2)
	v_mfma_f32_32x32x16_bf16 v[114:129], v[234:237], v[130:133], v[114:129]
	ds_read_b128 v[234:237], v220 offset:0x100
	v_mfma_f32_32x32x16_bf16 v[82:97], v[238:241], v[130:133], v[82:97]
	ds_read_b128 v[238:241], v220 offset:0x3100
	s_waitcnt lgkmcnt(2)
	v_mfma_f32_32x32x16_bf16 v[114:129], v[230:233], v[192:195], v[114:129]
	ds_read_b128 v[230:233], v219 offset:0x100
	v_mfma_f32_32x32x16_bf16 v[82:97], v[242:245], v[192:195], v[82:97]
	ds_read_b128 v[242:245], v219 offset:0x3100
	ds_read_b128 v[246:249], v199 offset:0x800
	s_waitcnt lgkmcnt(3)
	v_mfma_f32_32x32x16_bf16 v[114:129], v[234:237], v[202:205], v[114:129]
	ds_read_b128 v[234:237], v218 offset:0x100
	v_mfma_f32_32x32x16_bf16 v[82:97], v[238:241], v[202:205], v[82:97]
	ds_read_b128 v[238:241], v218 offset:0x3100
	ds_read_b128 v[250:253], v199 offset:0xc00
	s_waitcnt lgkmcnt(3)
	v_mfma_f32_32x32x16_bf16 v[114:129], v[230:233], v[246:249], v[114:129]
	s_waitcnt lgkmcnt(0)
	v_mfma_f32_32x32x16_bf16 v[82:97], v[242:245], v[246:249], v[82:97]
	v_mfma_f32_32x32x16_bf16 v[114:129], v[234:237], v[250:253], v[114:129]
	v_mfma_f32_32x32x16_bf16 v[82:97], v[238:241], v[250:253], v[82:97]
	v_exp_f32_e32 v66, v66
	v_exp_f32_e32 v67, v67
	v_exp_f32_e32 v68, v68
	v_exp_f32_e32 v69, v69
	v_exp_f32_e32 v70, v70
	v_exp_f32_e32 v71, v71
	v_exp_f32_e32 v72, v72
	v_exp_f32_e32 v73, v73
	v_add_f32_e32 v166, v168, v176
	v_add_f32_e32 v179, v175, v178
	v_add_f32_e32 v180, v169, v167
	v_add_f32_e32 v181, v174, v177
	v_exp_f32_e32 v74, v74
	v_exp_f32_e32 v75, v75
	v_exp_f32_e32 v76, v76
	v_exp_f32_e32 v77, v77
	v_add_f32_e32 v166, v170, v166
	v_add_f32_e32 v179, v173, v179
	v_add_f32_e32 v180, v165, v180
	v_add_f32_e32 v181, v171, v181
	v_exp_f32_e32 v78, v78
	v_exp_f32_e32 v79, v79
	v_exp_f32_e32 v80, v80
	v_exp_f32_e32 v81, v81
	v_add_f32_e32 v166, v163, v166
	v_add_f32_e32 v179, v172, v179
	v_add_f32_e32 v180, v162, v180
	v_add_f32_e32 v181, v164, v181
	v_add_f32_e32 v166, v66, v166
	v_add_f32_e32 v179, v67, v179
	v_add_f32_e32 v180, v68, v180
	v_add_f32_e32 v181, v69, v181
	v_add_f32_e32 v166, v70, v166
	v_add_f32_e32 v179, v71, v179
	v_add_f32_e32 v180, v72, v180
	v_add_f32_e32 v181, v73, v181
	v_add_f32_e32 v166, v74, v166
	v_add_f32_e32 v179, v75, v179
	v_add_f32_e32 v180, v76, v180
	v_add_f32_e32 v181, v77, v181
	v_add_f32_e32 v166, v78, v166
	v_add_f32_e32 v179, v79, v179
	v_add_f32_e32 v180, v80, v180
	v_add_f32_e32 v181, v81, v181
	v_add_f32_e32 v166, v166, v179
	v_add_f32_e32 v179, v180, v181
	v_add_f32_e32 v223, v166, v179
	v_mov_b32_e32 v224, v223
	v_cvt_pk_bf16_f32 v166, v176, v178
	v_cvt_pk_bf16_f32 v167, v167, v177
	v_cvt_pk_bf16_f32 v168, v168, v175
	s_nop 1
	v_permlane32_swap_b32_e32 v223, v224
	v_cvt_pk_bf16_f32 v169, v169, v174
	v_cvt_pk_bf16_f32 v170, v170, v173
	v_cvt_pk_bf16_f32 v171, v165, v171
	v_cvt_pk_bf16_f32 v172, v163, v172
	v_cvt_pk_bf16_f32 v173, v162, v164
	v_cvt_pk_bf16_f32 v174, v66, v67
	v_cvt_pk_bf16_f32 v175, v68, v69
	v_cvt_pk_bf16_f32 v176, v70, v71
	v_cvt_pk_bf16_f32 v177, v72, v73
	v_cvt_pk_bf16_f32 v178, v74, v75
	v_cvt_pk_bf16_f32 v179, v76, v77
	v_cvt_pk_bf16_f32 v180, v78, v79
	v_cvt_pk_bf16_f32 v181, v80, v81
	v_lshl_add_u64 v[190:191], s[42:43], 0, v[188:189]
	v_add_co_u32_e32 v70, vcc, s49, v190
	v_lshl_add_u64 v[196:197], s[42:43], 0, v[186:187]
	s_nop 0
	v_addc_co_u32_e32 v71, vcc, 0, v191, vcc
	v_add_co_u32_e32 v74, vcc, s28, v190
	s_nop 1
	v_addc_co_u32_e32 v75, vcc, 0, v191, vcc
	global_load_dwordx4 v[66:69], v[70:71], off offset:256
	s_nop 0
	global_load_dwordx4 v[70:73], v[70:71], off
	s_nop 0
	global_load_dwordx4 v[78:81], v[74:75], off offset:256
	s_nop 0
	global_load_dwordx4 v[74:77], v[74:75], off
	v_add_co_u32_e32 v162, vcc, s68, v196
	s_nop 1
	v_addc_co_u32_e32 v163, vcc, 0, v197, vcc
	global_load_dwordx4 v[162:165], v[162:163], off
	ds_read_b64_tr_b16 v[230:231], v201 offset:0
	ds_read_b64_tr_b16 v[232:233], v201 offset:0x800
	ds_read_b64_tr_b16 v[234:235], v201 offset:0x1000
	ds_read_b64_tr_b16 v[236:237], v201 offset:0x1800
	ds_read_b64_tr_b16 v[238:239], v201 offset:0x2000
	ds_read_b64_tr_b16 v[240:241], v201 offset:0x2800
	ds_read_b64_tr_b16 v[242:243], v201 offset:0x3000
	ds_read_b64_tr_b16 v[244:245], v201 offset:0x3800
	ds_read_b64_tr_b16 v[246:247], v201 offset:0x200
	ds_read_b64_tr_b16 v[248:249], v201 offset:0xa00
	s_waitcnt lgkmcnt(8)
; __device__ __forceinline__ void pv_d0(f32x16* o, int vb, bf16x8 pa0, bf16x8 pa1, bf16x8 pa2, bf16x8 pa3) {
;     ...
;   const s16x4 l0 = tr_read<v_rd_off(0, 0, 0)>(vb), h0 = tr_read<v_rd_off(0, 0, 1)>(vb);
;   const s16x4 l1 = tr_read<v_rd_off(0, 1, 0)>(vb), h1 = tr_read<v_rd_off(0, 1, 1)>(vb);
;   const s16x4 l2 = tr_read<v_rd_off(0, 2, 0)>(vb), h2 = tr_read<v_rd_off(0, 2, 1)>(vb);
;   const s16x4 l3 = tr_read<v_rd_off(0, 3, 0)>(vb), h3 = tr_read<v_rd_off(0, 3, 1)>(vb);
;   const s16x4 l4 = tr_read<v_rd_off(1, 0, 0)>(vb), h4 = tr_read<v_rd_off(1, 0, 1)>(vb);
;   asm volatile("s_waitcnt lgkmcnt(8)" ::: "memory"); SBAR();
;   o[0] = __builtin_amdgcn_mfma_f32_32x32x16_bf16(pa0, PK(l0, h0), o[0], 0, 0, 0);
;   const s16x4 l5 = tr_read<v_rd_off(1, 1, 0)>(vb), h5 = tr_read<v_rd_off(1, 1, 1)>(vb);
;   asm volatile("s_waitcnt lgkmcnt(8)" ::: "memory"); SBAR();
;   o[0] = __builtin_amdgcn_mfma_f32_32x32x16_bf16(pa1, PK(l1, h1), o[0], 0, 0, 0);
;   const s16x4 l6 = tr_read<v_rd_off(1, 2, 0)>(vb), h6 = tr_read<v_rd_off(1, 2, 1)>(vb);
;   asm volatile("s_waitcnt lgkmcnt(8)" ::: "memory"); SBAR();
;   o[0] = __builtin_amdgcn_mfma_f32_32x32x16_bf16(pa2, PK(l2, h2), o[0], 0, 0, 0);
;   const s16x4 l7 = tr_read<v_rd_off(1, 3, 0)>(vb), h7 = tr_read<v_rd_off(1, 3, 1)>(vb);
;   asm volatile("s_waitcnt lgkmcnt(8)" ::: "memory"); SBAR();
;   o[0] = __builtin_amdgcn_mfma_f32_32x32x16_bf16(pa3, PK(l3, h3), o[0], 0, 0, 0);
;   const s16x4 l8 = tr_read<v_rd_off(2, 0, 0)>(vb), h8 = tr_read<v_rd_off(2, 0, 1)>(vb);
;   asm volatile("s_waitcnt lgkmcnt(8)" ::: "memory"); SBAR();
;   o[1] = __builtin_amdgcn_mfma_f32_32x32x16_bf16(pa0, PK(l4, h4), o[1], 0, 0, 0);
;   const s16x4 l9 = tr_read<v_rd_off(2, 1, 0)>(vb), h9 = tr_read<v_rd_off(2, 1, 1)>(vb);
;   asm volatile("s_waitcnt lgkmcnt(8)" ::: "memory"); SBAR();
;   o[1] = __builtin_amdgcn_mfma_f32_32x32x16_bf16(pa1, PK(l5, h5), o[1], 0, 0, 0);
;   const s16x4 l10 = tr_read<v_rd_off(2, 2, 0)>(vb), h10 = tr_read<v_rd_off(2, 2, 1)>(vb);
;   asm volatile("s_waitcnt lgkmcnt(8)" ::: "memory"); SBAR();
;   o[1] = __builtin_amdgcn_mfma_f32_32x32x16_bf16(pa2, PK(l6, h6), o[1], 0, 0, 0);
;   const s16x4 l11 = tr_read<v_rd_off(2, 3, 0)>(vb), h11 = tr_read<v_rd_off(2, 3, 1)>(vb);
;   asm volatile("s_waitcnt lgkmcnt(8)" ::: "memory"); SBAR();
;   o[1] = __builtin_amdgcn_mfma_f32_32x32x16_bf16(pa3, PK(l7, h7), o[1], 0, 0, 0);
	s_nop 0
	v_mfma_f32_32x32x16_bf16 v[2:17], v[166:169], v[230:233], v[2:17]
	ds_read_b64_tr_b16 v[230:231], v201 offset:0x1200
	ds_read_b64_tr_b16 v[232:233], v201 offset:0x1a00
	s_waitcnt lgkmcnt(8)
	v_mfma_f32_32x32x16_bf16 v[2:17], v[170:173], v[234:237], v[2:17]
	ds_read_b64_tr_b16 v[234:235], v201 offset:0x2200
	ds_read_b64_tr_b16 v[236:237], v201 offset:0x2a00
	s_waitcnt lgkmcnt(8)
	v_mfma_f32_32x32x16_bf16 v[2:17], v[174:177], v[238:241], v[2:17]
	ds_read_b64_tr_b16 v[238:239], v201 offset:0x3200
	ds_read_b64_tr_b16 v[240:241], v201 offset:0x3a00
	s_waitcnt lgkmcnt(8)
	v_mfma_f32_32x32x16_bf16 v[2:17], v[178:181], v[242:245], v[2:17]
	ds_read_b64_tr_b16 v[242:243], v201 offset:0x400
	ds_read_b64_tr_b16 v[244:245], v201 offset:0xc00
	s_waitcnt lgkmcnt(8)
	v_mfma_f32_32x32x16_bf16 v[50:65], v[166:169], v[246:249], v[50:65]
	ds_read_b64_tr_b16 v[246:247], v201 offset:0x1400
	ds_read_b64_tr_b16 v[248:249], v201 offset:0x1c00
	s_waitcnt lgkmcnt(8)
	v_mfma_f32_32x32x16_bf16 v[50:65], v[170:173], v[230:233], v[50:65]
	ds_read_b64_tr_b16 v[230:231], v201 offset:0x2400
	ds_read_b64_tr_b16 v[232:233], v201 offset:0x2c00
	s_waitcnt lgkmcnt(8)
	v_mfma_f32_32x32x16_bf16 v[50:65], v[174:177], v[234:237], v[50:65]
	ds_read_b64_tr_b16 v[234:235], v201 offset:0x3400
	ds_read_b64_tr_b16 v[236:237], v201 offset:0x3c00
	s_waitcnt lgkmcnt(8)
	v_mfma_f32_32x32x16_bf16 v[50:65], v[178:181], v[238:241], v[50:65]
	ds_read_b64_tr_b16 v[238:239], v201 offset:0x600
	ds_read_b64_tr_b16 v[240:241], v201 offset:0xe00
	s_waitcnt lgkmcnt(8)
	v_mfma_f32_32x32x16_bf16 v[34:49], v[166:169], v[242:245], v[34:49]
	ds_read_b64_tr_b16 v[242:243], v201 offset:0x1600
	ds_read_b64_tr_b16 v[244:245], v201 offset:0x1e00
	s_waitcnt lgkmcnt(8)
	v_mfma_f32_32x32x16_bf16 v[34:49], v[170:173], v[246:249], v[34:49]
	ds_read_b64_tr_b16 v[246:247], v201 offset:0x2600
	ds_read_b64_tr_b16 v[248:249], v201 offset:0x2e00
	s_waitcnt lgkmcnt(8)
	v_mfma_f32_32x32x16_bf16 v[34:49], v[174:177], v[230:233], v[34:49]
	ds_read_b64_tr_b16 v[230:231], v201 offset:0x3600
	ds_read_b64_tr_b16 v[232:233], v201 offset:0x3e00
	s_waitcnt lgkmcnt(8)
	v_mfma_f32_32x32x16_bf16 v[34:49], v[178:181], v[234:237], v[34:49]
	s_waitcnt lgkmcnt(6)
	v_mfma_f32_32x32x16_bf16 v[18:33], v[166:169], v[238:241], v[18:33]
	s_waitcnt lgkmcnt(4)
	v_mfma_f32_32x32x16_bf16 v[18:33], v[170:173], v[242:245], v[18:33]
	s_waitcnt lgkmcnt(2)
	v_mfma_f32_32x32x16_bf16 v[18:33], v[174:177], v[246:249], v[18:33]
	s_waitcnt lgkmcnt(0)
	v_max_f32_e32 v166, v114, v118
	v_max_f32_e32 v167, v115, v119
	v_max_f32_e32 v168, v117, v121
	v_max3_f32 v169, v116, v120, v124
	v_max3_f32 v168, v168, v125, v129
	v_max3_f32 v166, v166, v122, v126
	v_max3_f32 v167, v167, v123, v127
	v_max3_f32 v169, v169, v128, v84
	v_max3_f32 v168, v168, v85, v89
	v_max3_f32 v166, v166, v82, v86
	v_max3_f32 v167, v167, v83, v87
	v_max3_f32 v169, v169, v88, v92
	v_max3_f32 v168, v168, v93, v97
	v_mfma_f32_32x32x16_bf16 v[18:33], v[178:181], v[230:233], v[18:33]
	v_max3_f32 v166, v166, v90, v94
	v_max3_f32 v167, v167, v91, v95
	v_max3_f32 v168, v169, v96, v168
	v_max3_f32 v166, v166, v167, v168
	v_cmp_ge_f32_e32 vcc, s48, v166
	s_cmp_eq_u64 vcc, exec
	s_cbranch_scc0 .LBB0_400
	v_mov_b32_e32 v227, v225
	v_mov_b32_e32 v226, 1.0

; __device__ __forceinline__ void qkt12_roll(f32x16& p0, f32x16& p1, const f32x16& negm, int kb, int qa, const bf16x8* qr) {
;   const int a0 = kb ^ (0 << 5); const bf16x8 x0 = lds_rd128<0>(a0), y0 = lds_rd128<12288>(a0);
;   const int a1 = kb ^ (1 << 5); const bf16x8 x1 = lds_rd128<0>(a1), y1 = lds_rd128<12288>(a1);
;   asm volatile("s_waitcnt lgkmcnt(2)" ::: "memory"); SBAR();
;   p0 = __builtin_amdgcn_mfma_f32_32x32x16_bf16(x0, qr[0], negm, 0, 0, 0); p1 = __builtin_amdgcn_mfma_f32_32x32x16_bf16(y0, qr[0], negm, 0, 0, 0);
;   const int a2 = kb ^ (2 << 5); const bf16x8 x2 = lds_rd128<0>(a2), y2 = lds_rd128<12288>(a2);
;   asm volatile("s_waitcnt lgkmcnt(2)" ::: "memory"); SBAR();
;   p0 = __builtin_amdgcn_mfma_f32_32x32x16_bf16(x1, qr[1], p0, 0, 0, 0); p1 = __builtin_amdgcn_mfma_f32_32x32x16_bf16(y1, qr[1], p1, 0, 0, 0);
;   const int a3 = kb ^ (3 << 5); const bf16x8 x3 = lds_rd128<0>(a3), y3 = lds_rd128<12288>(a3);
;   asm volatile("s_waitcnt lgkmcnt(2)" ::: "memory"); SBAR();
;   p0 = __builtin_amdgcn_mfma_f32_32x32x16_bf16(x2, qr[2], p0, 0, 0, 0); p1 = __builtin_amdgcn_mfma_f32_32x32x16_bf16(y2, qr[2], p1, 0, 0, 0);
;   const int a4 = kb ^ (0 << 5); const bf16x8 x4 = lds_rd128<128>(a4), y4 = lds_rd128<12416>(a4);
;   asm volatile("s_waitcnt lgkmcnt(2)" ::: "memory"); SBAR();
;   p0 = __builtin_amdgcn_mfma_f32_32x32x16_bf16(x3, qr[3], p0, 0, 0, 0); p1 = __builtin_amdgcn_mfma_f32_32x32x16_bf16(y3, qr[3], p1, 0, 0, 0);
;   const int a5 = kb ^ (1 << 5); const bf16x8 x5 = lds_rd128<128>(a5), y5 = lds_rd128<12416>(a5);
;   asm volatile("s_waitcnt lgkmcnt(2)" ::: "memory"); SBAR();
;   p0 = __builtin_amdgcn_mfma_f32_32x32x16_bf16(x4, qr[4], p0, 0, 0, 0); p1 = __builtin_amdgcn_mfma_f32_32x32x16_bf16(y4, qr[4], p1, 0, 0, 0);
;   const int a6 = kb ^ (2 << 5); const bf16x8 x6 = lds_rd128<128>(a6), y6 = lds_rd128<12416>(a6);
;   asm volatile("s_waitcnt lgkmcnt(2)" ::: "memory"); SBAR();
;   p0 = __builtin_amdgcn_mfma_f32_32x32x16_bf16(x5, qr[5], p0, 0, 0, 0); p1 = __builtin_amdgcn_mfma_f32_32x32x16_bf16(y5, qr[5], p1, 0, 0, 0);
;   const int a7 = kb ^ (3 << 5); const bf16x8 x7 = lds_rd128<128>(a7), y7 = lds_rd128<12416>(a7);
;   asm volatile("s_waitcnt lgkmcnt(2)" ::: "memory"); SBAR();
;   p0 = __builtin_amdgcn_mfma_f32_32x32x16_bf16(x6, qr[6], p0, 0, 0, 0); p1 = __builtin_amdgcn_mfma_f32_32x32x16_bf16(y6, qr[6], p1, 0, 0, 0);
.Lmy_negm_skip_1:
	v_exp_f32_e32 v177, v115
	v_exp_f32_e32 v176, v117
	v_exp_f32_e32 v168, v118
	v_exp_f32_e32 v175, v119
	v_exp_f32_e32 v169, v120
	v_exp_f32_e32 v174, v121
	v_exp_f32_e32 v170, v122
	v_exp_f32_e32 v173, v123
	v_exp_f32_e32 v171, v125
	v_exp_f32_e32 v172, v127
	s_waitcnt lgkmcnt(0)
	s_barrier
	ds_read_b128 v[66:69], v209 offset:0
	ds_read_b128 v[178:181], v209 offset:0x3000
	ds_read_b128 v[230:233], v215 offset:0
	ds_read_b128 v[234:237], v215 offset:0x3000
	s_waitcnt lgkmcnt(2)
	s_nop 0
	v_mfma_f32_32x32x16_bf16 v[114:129], v[66:69], v[158:161], v[98:113]
	v_mfma_f32_32x32x16_bf16 v[66:81], v[178:181], v[158:161], v[98:113]
	ds_read_b128 v[178:181], v216 offset:0
	ds_read_b128 v[238:241], v216 offset:0x3000
	s_waitcnt lgkmcnt(2)
	v_mfma_f32_32x32x16_bf16 v[114:129], v[230:233], v[154:157], v[114:129]
	ds_read_b128 v[230:233], v217 offset:0
	v_mfma_f32_32x32x16_bf16 v[66:81], v[234:237], v[154:157], v[66:81]
	ds_read_b128 v[234:237], v217 offset:0x3000
	s_waitcnt lgkmcnt(2)
	v_mfma_f32_32x32x16_bf16 v[114:129], v[178:181], v[150:153], v[114:129]
	ds_read_b128 v[178:181], v209 offset:0x80
	v_mfma_f32_32x32x16_bf16 v[66:81], v[238:241], v[150:153], v[66:81]
	ds_read_b128 v[238:241], v209 offset:0x3080
	s_waitcnt lgkmcnt(2)
	v_mfma_f32_32x32x16_bf16 v[114:129], v[230:233], v[146:149], v[114:129]
	ds_read_b128 v[230:233], v215 offset:0x80
	v_mfma_f32_32x32x16_bf16 v[66:81], v[234:237], v[146:149], v[66:81]
	ds_read_b128 v[234:237], v215 offset:0x3080
	s_waitcnt lgkmcnt(2)
	v_mfma_f32_32x32x16_bf16 v[114:129], v[178:181], v[142:145], v[114:129]
	ds_read_b128 v[178:181], v216 offset:0x80
	v_mfma_f32_32x32x16_bf16 v[66:81], v[238:241], v[142:145], v[66:81]
	ds_read_b128 v[238:241], v216 offset:0x3080
	s_waitcnt lgkmcnt(2)
	v_mfma_f32_32x32x16_bf16 v[114:129], v[230:233], v[138:141], v[114:129]
	ds_read_b128 v[230:233], v217 offset:0x80
	v_mfma_f32_32x32x16_bf16 v[66:81], v[234:237], v[138:141], v[66:81]
	ds_read_b128 v[234:237], v217 offset:0x3080
	s_waitcnt lgkmcnt(2)
	v_mfma_f32_32x32x16_bf16 v[114:129], v[178:181], v[134:137], v[114:129]
	ds_read_b128 v[178:181], v209 offset:0x100
	v_mfma_f32_32x32x16_bf16 v[66:81], v[238:241], v[134:137], v[66:81]
	ds_read_b128 v[238:241], v209 offset:0x3100
	s_waitcnt lgkmcnt(2)
	v_mfma_f32_32x32x16_bf16 v[114:129], v[230:233], v[130:133], v[114:129]
	ds_read_b128 v[230:233], v215 offset:0x100
	v_mfma_f32_32x32x16_bf16 v[66:81], v[234:237], v[130:133], v[66:81]
	ds_read_b128 v[234:237], v215 offset:0x3100
	s_waitcnt lgkmcnt(2)
	v_mfma_f32_32x32x16_bf16 v[114:129], v[178:181], v[192:195], v[114:129]
	ds_read_b128 v[178:181], v216 offset:0x100
	v_mfma_f32_32x32x16_bf16 v[66:81], v[238:241], v[192:195], v[66:81]
	ds_read_b128 v[238:241], v216 offset:0x3100
	ds_read_b128 v[242:245], v199 offset:0x800
	s_waitcnt lgkmcnt(3)
	v_mfma_f32_32x32x16_bf16 v[114:129], v[230:233], v[202:205], v[114:129]
	ds_read_b128 v[230:233], v217 offset:0x100
	v_mfma_f32_32x32x16_bf16 v[66:81], v[234:237], v[202:205], v[66:81]
	ds_read_b128 v[234:237], v217 offset:0x3100
	ds_read_b128 v[246:249], v199 offset:0xc00
	s_waitcnt lgkmcnt(3)
	v_mfma_f32_32x32x16_bf16 v[114:129], v[178:181], v[242:245], v[114:129]
	s_waitcnt lgkmcnt(0)
	v_mfma_f32_32x32x16_bf16 v[66:81], v[238:241], v[242:245], v[66:81]
	v_mfma_f32_32x32x16_bf16 v[114:129], v[230:233], v[246:249], v[114:129]
	v_mfma_f32_32x32x16_bf16 v[66:81], v[234:237], v[246:249], v[66:81]
	v_exp_f32_e32 v82, v82
	v_exp_f32_e32 v83, v83
	v_exp_f32_e32 v84, v84
	v_exp_f32_e32 v85, v85
	v_exp_f32_e32 v86, v86
	v_exp_f32_e32 v87, v87
	v_exp_f32_e32 v88, v88
	v_exp_f32_e32 v89, v89
	v_add_f32_e32 v178, v168, v166
	v_add_f32_e32 v179, v175, v177
	v_add_f32_e32 v180, v169, v167
	v_add_f32_e32 v181, v174, v176
	v_exp_f32_e32 v90, v90
	v_exp_f32_e32 v91, v91
	v_exp_f32_e32 v92, v92
	v_exp_f32_e32 v93, v93
	v_add_f32_e32 v178, v170, v178
	v_add_f32_e32 v179, v173, v179
	v_add_f32_e32 v180, v165, v180
	v_add_f32_e32 v181, v171, v181
	v_exp_f32_e32 v94, v94
	v_exp_f32_e32 v95, v95
	v_exp_f32_e32 v96, v96
	v_exp_f32_e32 v97, v97
	v_add_f32_e32 v178, v163, v178
	v_add_f32_e32 v179, v172, v179
	v_add_f32_e32 v180, v162, v180
	v_add_f32_e32 v181, v164, v181
	v_add_f32_e32 v178, v82, v178
	v_add_f32_e32 v179, v179, v83
	v_add_f32_e32 v180, v180, v84
	v_add_f32_e32 v181, v181, v85
	v_add_f32_e32 v178, v86, v178
	v_add_f32_e32 v179, v87, v179
	v_add_f32_e32 v180, v88, v180
	v_add_f32_e32 v181, v89, v181
	v_add_f32_e32 v178, v90, v178
	v_add_f32_e32 v179, v91, v179
	v_add_f32_e32 v180, v92, v180
	v_add_f32_e32 v181, v93, v181
	v_add_f32_e32 v178, v94, v178
	v_add_f32_e32 v179, v95, v179
	v_add_f32_e32 v180, v96, v180
	v_add_f32_e32 v181, v97, v181
	v_add_f32_e32 v178, v178, v179
	v_add_f32_e32 v179, v180, v181
	v_add_f32_e32 v229, v178, v179
	v_mov_b32_e32 v230, v229
	v_cvt_pk_bf16_f32 v166, v166, v177
	v_cvt_pk_bf16_f32 v167, v167, v176
	v_cvt_pk_bf16_f32 v168, v168, v175
	v_cvt_pk_bf16_f32 v169, v169, v174
	s_nop 1
	v_permlane32_swap_b32_e32 v229, v230
	v_cvt_pk_bf16_f32 v170, v170, v173
	v_cvt_pk_bf16_f32 v171, v165, v171
	v_cvt_pk_bf16_f32 v172, v163, v172
	v_cvt_pk_bf16_f32 v173, v162, v164
	v_cvt_pk_bf16_f32 v174, v82, v83
	v_cvt_pk_bf16_f32 v175, v84, v85
	v_cvt_pk_bf16_f32 v176, v86, v87
	v_cvt_pk_bf16_f32 v177, v88, v89
	v_cvt_pk_bf16_f32 v178, v90, v91
	v_cvt_pk_bf16_f32 v179, v92, v93
	v_cvt_pk_bf16_f32 v180, v94, v95
	v_cvt_pk_bf16_f32 v181, v96, v97
	s_nop 0
	v_add_co_u32_e32 v86, vcc, s69, v190
	s_nop 1
	v_addc_co_u32_e32 v87, vcc, 0, v191, vcc
	v_add_co_u32_e32 v90, vcc, s74, v190
	s_nop 1
	v_addc_co_u32_e32 v91, vcc, 0, v191, vcc
	global_load_dwordx4 v[82:85], v[86:87], off offset:256
	s_nop 0
	global_load_dwordx4 v[86:89], v[86:87], off
	s_nop 0
	global_load_dwordx4 v[94:97], v[90:91], off offset:256
	s_nop 0
	global_load_dwordx4 v[90:93], v[90:91], off
	v_add_co_u32_e32 v162, vcc, s75, v196
	s_nop 1
	v_addc_co_u32_e32 v163, vcc, 0, v197, vcc
	global_load_dwordx4 v[162:165], v[162:163], off
	ds_read_b64_tr_b16 v[232:233], v208 offset:0
	ds_read_b64_tr_b16 v[234:235], v208 offset:0x800
	ds_read_b64_tr_b16 v[236:237], v208 offset:0x1000
	ds_read_b64_tr_b16 v[238:239], v208 offset:0x1800
	ds_read_b64_tr_b16 v[240:241], v208 offset:0x2000
	ds_read_b64_tr_b16 v[242:243], v208 offset:0x2800
	ds_read_b64_tr_b16 v[244:245], v208 offset:0x3000
	ds_read_b64_tr_b16 v[246:247], v208 offset:0x3800
	ds_read_b64_tr_b16 v[248:249], v208 offset:0x200
	ds_read_b64_tr_b16 v[250:251], v208 offset:0xa00
	s_waitcnt lgkmcnt(8)
; __device__ __forceinline__ void pv_d0(f32x16* o, int vb, bf16x8 pa0, bf16x8 pa1, bf16x8 pa2, bf16x8 pa3) {
;     ...
;   const s16x4 l0 = tr_read<v_rd_off(0, 0, 0)>(vb), h0 = tr_read<v_rd_off(0, 0, 1)>(vb);
;   const s16x4 l1 = tr_read<v_rd_off(0, 1, 0)>(vb), h1 = tr_read<v_rd_off(0, 1, 1)>(vb);
;   const s16x4 l2 = tr_read<v_rd_off(0, 2, 0)>(vb), h2 = tr_read<v_rd_off(0, 2, 1)>(vb);
;   const s16x4 l3 = tr_read<v_rd_off(0, 3, 0)>(vb), h3 = tr_read<v_rd_off(0, 3, 1)>(vb);
;   const s16x4 l4 = tr_read<v_rd_off(1, 0, 0)>(vb), h4 = tr_read<v_rd_off(1, 0, 1)>(vb);
;   asm volatile("s_waitcnt lgkmcnt(8)" ::: "memory"); SBAR();
;   o[0] = __builtin_amdgcn_mfma_f32_32x32x16_bf16(pa0, PK(l0, h0), o[0], 0, 0, 0);
;   const s16x4 l5 = tr_read<v_rd_off(1, 1, 0)>(vb), h5 = tr_read<v_rd_off(1, 1, 1)>(vb);
;   asm volatile("s_waitcnt lgkmcnt(8)" ::: "memory"); SBAR();
;   o[0] = __builtin_amdgcn_mfma_f32_32x32x16_bf16(pa1, PK(l1, h1), o[0], 0, 0, 0);
;   const s16x4 l6 = tr_read<v_rd_off(1, 2, 0)>(vb), h6 = tr_read<v_rd_off(1, 2, 1)>(vb);
;   asm volatile("s_waitcnt lgkmcnt(8)" ::: "memory"); SBAR();
;   o[0] = __builtin_amdgcn_mfma_f32_32x32x16_bf16(pa2, PK(l2, h2), o[0], 0, 0, 0);
;   const s16x4 l7 = tr_read<v_rd_off(1, 3, 0)>(vb), h7 = tr_read<v_rd_off(1, 3, 1)>(vb);
;   asm volatile("s_waitcnt lgkmcnt(8)" ::: "memory"); SBAR();
;   o[0] = __builtin_amdgcn_mfma_f32_32x32x16_bf16(pa3, PK(l3, h3), o[0], 0, 0, 0);
;   const s16x4 l8 = tr_read<v_rd_off(2, 0, 0)>(vb), h8 = tr_read<v_rd_off(2, 0, 1)>(vb);
;   asm volatile("s_waitcnt lgkmcnt(8)" ::: "memory"); SBAR();
;   o[1] = __builtin_amdgcn_mfma_f32_32x32x16_bf16(pa0, PK(l4, h4), o[1], 0, 0, 0);
;   const s16x4 l9 = tr_read<v_rd_off(2, 1, 0)>(vb), h9 = tr_read<v_rd_off(2, 1, 1)>(vb);
;   asm volatile("s_waitcnt lgkmcnt(8)" ::: "memory"); SBAR();
;   o[1] = __builtin_amdgcn_mfma_f32_32x32x16_bf16(pa1, PK(l5, h5), o[1], 0, 0, 0);
;   const s16x4 l10 = tr_read<v_rd_off(2, 2, 0)>(vb), h10 = tr_read<v_rd_off(2, 2, 1)>(vb);
;   asm volatile("s_waitcnt lgkmcnt(8)" ::: "memory"); SBAR();
;   o[1] = __builtin_amdgcn_mfma_f32_32x32x16_bf16(pa2, PK(l6, h6), o[1], 0, 0, 0);
;   const s16x4 l11 = tr_read<v_rd_off(2, 3, 0)>(vb), h11 = tr_read<v_rd_off(2, 3, 1)>(vb);
;   asm volatile("s_waitcnt lgkmcnt(8)" ::: "memory"); SBAR();
;   o[1] = __builtin_amdgcn_mfma_f32_32x32x16_bf16(pa3, PK(l7, h7), o[1], 0, 0, 0);
	s_nop 0
	v_mfma_f32_32x32x16_bf16 v[2:17], v[166:169], v[232:235], v[2:17]
	ds_read_b64_tr_b16 v[232:233], v208 offset:0x1200
	ds_read_b64_tr_b16 v[234:235], v208 offset:0x1a00
	s_waitcnt lgkmcnt(8)
	v_mfma_f32_32x32x16_bf16 v[2:17], v[170:173], v[236:239], v[2:17]
	ds_read_b64_tr_b16 v[236:237], v208 offset:0x2200
	ds_read_b64_tr_b16 v[238:239], v208 offset:0x2a00
	s_waitcnt lgkmcnt(8)
	v_mfma_f32_32x32x16_bf16 v[2:17], v[174:177], v[240:243], v[2:17]
	ds_read_b64_tr_b16 v[240:241], v208 offset:0x3200
	ds_read_b64_tr_b16 v[242:243], v208 offset:0x3a00
	s_waitcnt lgkmcnt(8)
	v_mfma_f32_32x32x16_bf16 v[2:17], v[178:181], v[244:247], v[2:17]
	ds_read_b64_tr_b16 v[244:245], v208 offset:0x400
	ds_read_b64_tr_b16 v[246:247], v208 offset:0xc00
	s_waitcnt lgkmcnt(8)
	v_mfma_f32_32x32x16_bf16 v[50:65], v[166:169], v[248:251], v[50:65]
	ds_read_b64_tr_b16 v[248:249], v208 offset:0x1400
	ds_read_b64_tr_b16 v[250:251], v208 offset:0x1c00
	s_waitcnt lgkmcnt(8)
	v_mfma_f32_32x32x16_bf16 v[50:65], v[170:173], v[232:235], v[50:65]
	ds_read_b64_tr_b16 v[232:233], v208 offset:0x2400
	ds_read_b64_tr_b16 v[234:235], v208 offset:0x2c00
	s_waitcnt lgkmcnt(8)
	v_mfma_f32_32x32x16_bf16 v[50:65], v[174:177], v[236:239], v[50:65]
	ds_read_b64_tr_b16 v[236:237], v208 offset:0x3400
	ds_read_b64_tr_b16 v[238:239], v208 offset:0x3c00
	s_waitcnt lgkmcnt(8)
	v_mfma_f32_32x32x16_bf16 v[50:65], v[178:181], v[240:243], v[50:65]
	ds_read_b64_tr_b16 v[240:241], v208 offset:0x600
	ds_read_b64_tr_b16 v[242:243], v208 offset:0xe00
	s_waitcnt lgkmcnt(8)
	v_mfma_f32_32x32x16_bf16 v[34:49], v[166:169], v[244:247], v[34:49]
	ds_read_b64_tr_b16 v[244:245], v208 offset:0x1600
	ds_read_b64_tr_b16 v[246:247], v208 offset:0x1e00
	s_waitcnt lgkmcnt(8)
	v_mfma_f32_32x32x16_bf16 v[34:49], v[170:173], v[248:251], v[34:49]
	ds_read_b64_tr_b16 v[248:249], v208 offset:0x2600
	ds_read_b64_tr_b16 v[250:251], v208 offset:0x2e00
	s_waitcnt lgkmcnt(8)
	v_mfma_f32_32x32x16_bf16 v[34:49], v[174:177], v[232:235], v[34:49]
	ds_read_b64_tr_b16 v[232:233], v208 offset:0x3600
	ds_read_b64_tr_b16 v[234:235], v208 offset:0x3e00
	s_waitcnt lgkmcnt(8)
	v_mfma_f32_32x32x16_bf16 v[34:49], v[178:181], v[236:239], v[34:49]
	s_waitcnt lgkmcnt(6)
	v_mfma_f32_32x32x16_bf16 v[18:33], v[166:169], v[240:243], v[18:33]
	s_waitcnt lgkmcnt(4)
	v_mfma_f32_32x32x16_bf16 v[18:33], v[170:173], v[244:247], v[18:33]
	s_waitcnt lgkmcnt(2)
	v_mfma_f32_32x32x16_bf16 v[18:33], v[174:177], v[248:251], v[18:33]
	s_waitcnt lgkmcnt(0)
	v_max_f32_e32 v166, v114, v118
	v_max_f32_e32 v167, v115, v119
	v_max_f32_e32 v168, v117, v121
	v_max3_f32 v169, v116, v120, v124
	v_max3_f32 v168, v168, v125, v129
	v_max3_f32 v166, v166, v122, v126
	v_max3_f32 v167, v167, v123, v127
	v_max3_f32 v169, v169, v128, v68
	v_max3_f32 v168, v168, v69, v73
	v_max3_f32 v166, v166, v66, v70
	v_max3_f32 v167, v167, v67, v71
	v_max3_f32 v169, v169, v72, v76
	v_max3_f32 v168, v168, v77, v81
	v_mfma_f32_32x32x16_bf16 v[18:33], v[178:181], v[232:235], v[18:33]
	v_max3_f32 v166, v166, v74, v78
	v_max3_f32 v167, v167, v75, v79
	v_max3_f32 v168, v169, v80, v168
	v_max3_f32 v166, v166, v167, v168
	v_mov_b32_e32 v167, v166
	v_cmp_ge_f32_e32 vcc, s48, v167
	s_cmp_eq_u64 vcc, exec
	v_mov_b32_e32 v166, 1.0
	s_cbranch_scc0 .LBB0_401
	v_mov_b32_e32 v225, v227
